# baseline (speedup 1.0000x reference)
; #define LAS __attribute__((address_space(3)))
; __device__ __forceinline__ void prologue(const Frame& F, const Args& a) {
;     ...
;         for (int item = gw; item < 1536; item += NGW) {
;             const int layer = item / 768, rem = item % 768, cc = rem >> 2, ks = rem & 3;
;             const int col = cc * 64 + F.lane;
;             const float* wp = a.in[5] + (size_t)layer * DM * NMOD + (size_t)(ks * 512) * NMOD + col;
;             float acc[9];
; #pragma unroll
;             for (int r = 0; r < 9; ++r) acc[r] = 0.f;
;             for (int k = 0; k < 512; k += 8) {
;                 float w[8];
; #pragma unroll
;                 for (int j = 0; j < 8; ++j) w[j] = wp[(size_t)(k + j) * NMOD];
; #pragma unroll
;                 for (int r = 0; r < 9; ++r) {
;                     const f32x4 s0 = *(const LAS f32x4*)(sl + r * DM + ks * 512 + k), s1 = *(const LAS f32x4*)(sl + r * DM + ks * 512 + k + 4);
;                     acc[r] += s0[0] * w[0] + s0[1] * w[1] + s0[2] * w[2] + s0[3] * w[3] + s1[0] * w[4] + s1[1] * w[5] + s1[2] * w[6] + s1[3] * w[7];
;                 }
;             }
.LBB0_25:
	s_mul_hi_i32 s6, s11, 0x2aaaaaab
	s_lshr_b32 s7, s6, 31
	s_ashr_i32 s54, s6, 7
	s_add_i32 s54, s54, s7
	s_mul_i32 s6, s54, 0x300
	s_sub_i32 s6, s11, s6
	s_and_b32 s55, s6, 3
	s_lshl_b32 s6, s6, 4
	s_andn2_b32 s6, s6, 63
	s_mul_i32 s7, s54, 0x6000000
	v_or_b32_e32 v8, s6, v164
	s_mul_hi_i32 s6, s54, 0x6000000
	s_add_u32 s7, s62, s7
	s_addc_u32 s6, s63, s6
	s_mul_i32 s34, s55, 0x1800000
	s_add_u32 s58, s7, s34
	v_ashrrev_i32_e32 v9, 31, v8
	s_addc_u32 s59, s6, 0
	s_mov_b64 s[68:69], s[58:59]
	s_lshl_b32 s6, s55, 11
	v_mov_b32_e32 v6, 0
	v_lshl_add_u64 v[10:11], v[8:9], 2, s[58:59]
	s_add_i32 s58, s6, 0
	s_mov_b32 s59, -8
	v_mov_b32_e32 v7, v6
	v_mov_b32_e32 v4, v6
	v_mov_b32_e32 v5, v6
	v_mov_b32_e32 v2, v6
	v_mov_b32_e32 v3, v6
	v_mov_b32_e32 v0, v6
	v_mov_b32_e32 v1, v6
	v_mov_b32_e32 v13, v6
	v_lshlrev_b32_e32 v104, 2, v8
	s_mov_b32 s59, 0
	global_load_dword v86, v104, s[68:69]
	s_add_u32 s68, s68, 0xc000
	s_addc_u32 s69, s69, 0
	global_load_dword v87, v104, s[68:69]
	s_add_u32 s68, s68, 0xc000
	s_addc_u32 s69, s69, 0
	global_load_dword v88, v104, s[68:69]
	s_add_u32 s68, s68, 0xc000
	s_addc_u32 s69, s69, 0
	global_load_dword v89, v104, s[68:69]
	s_add_u32 s68, s68, 0xc000
	s_addc_u32 s69, s69, 0
	global_load_dword v90, v104, s[68:69]
	s_add_u32 s68, s68, 0xc000
	s_addc_u32 s69, s69, 0
	global_load_dword v91, v104, s[68:69]
	s_add_u32 s68, s68, 0xc000
	s_addc_u32 s69, s69, 0
	global_load_dword v92, v104, s[68:69]
	s_add_u32 s68, s68, 0xc000
	s_addc_u32 s69, s69, 0
	global_load_dword v93, v104, s[68:69]
	s_add_u32 s68, s68, 0xc000
	s_addc_u32 s69, s69, 0
	global_load_dword v94, v104, s[68:69]
	s_add_u32 s68, s68, 0xc000
	s_addc_u32 s69, s69, 0
	global_load_dword v95, v104, s[68:69]
	s_add_u32 s68, s68, 0xc000
	s_addc_u32 s69, s69, 0
	global_load_dword v96, v104, s[68:69]
	s_add_u32 s68, s68, 0xc000
	s_addc_u32 s69, s69, 0
	global_load_dword v97, v104, s[68:69]
	s_add_u32 s68, s68, 0xc000
	s_addc_u32 s69, s69, 0
	global_load_dword v98, v104, s[68:69]
	s_add_u32 s68, s68, 0xc000
	s_addc_u32 s69, s69, 0
	global_load_dword v99, v104, s[68:69]
	s_add_u32 s68, s68, 0xc000
	s_addc_u32 s69, s69, 0
	global_load_dword v100, v104, s[68:69]
	s_add_u32 s68, s68, 0xc000
	s_addc_u32 s69, s69, 0
	global_load_dword v101, v104, s[68:69]
	s_add_u32 s68, s68, 0xc000
	s_addc_u32 s69, s69, 0
	global_load_dword v107, v104, s[68:69]
	s_add_u32 s68, s68, 0xc000
	s_addc_u32 s69, s69, 0
	global_load_dword v108, v104, s[68:69]
	s_add_u32 s68, s68, 0xc000
	s_addc_u32 s69, s69, 0
	global_load_dword v109, v104, s[68:69]
	s_add_u32 s68, s68, 0xc000
	s_addc_u32 s69, s69, 0
	global_load_dword v110, v104, s[68:69]
	s_add_u32 s68, s68, 0xc000
	s_addc_u32 s69, s69, 0
	global_load_dword v111, v104, s[68:69]
	s_add_u32 s68, s68, 0xc000
	s_addc_u32 s69, s69, 0
	global_load_dword v112, v104, s[68:69]
	s_add_u32 s68, s68, 0xc000
	s_addc_u32 s69, s69, 0
	global_load_dword v113, v104, s[68:69]
	s_add_u32 s68, s68, 0xc000
	s_addc_u32 s69, s69, 0
	global_load_dword v114, v104, s[68:69]
	s_add_u32 s68, s68, 0xc000
	s_addc_u32 s69, s69, 0
.LBB0_26:
	global_load_dword v115, v104, s[68:69]
	s_add_u32 s68, s68, 0xc000
	s_addc_u32 s69, s69, 0
	global_load_dword v116, v104, s[68:69]
	s_add_u32 s68, s68, 0xc000
	s_addc_u32 s69, s69, 0
	global_load_dword v117, v104, s[68:69]
	s_add_u32 s68, s68, 0xc000
	s_addc_u32 s69, s69, 0
	global_load_dword v118, v104, s[68:69]
	s_add_u32 s68, s68, 0xc000
	s_addc_u32 s69, s69, 0
	global_load_dword v119, v104, s[68:69]
	s_add_u32 s68, s68, 0xc000
	s_addc_u32 s69, s69, 0
	global_load_dword v120, v104, s[68:69]
	s_add_u32 s68, s68, 0xc000
	s_addc_u32 s69, s69, 0
	global_load_dword v121, v104, s[68:69]
	s_add_u32 s68, s68, 0xc000
	s_addc_u32 s69, s69, 0
	global_load_dword v122, v104, s[68:69]
	s_add_u32 s68, s68, 0xc000
	s_addc_u32 s69, s69, 0
	v_mov_b32_e32 v105, s58
	s_add_i32 s6, s58, 0x10000
	v_mov_b32_e32 v106, s6
	ds_read_b128 v[14:17], v105
	ds_read_b128 v[18:21], v105 offset:16
	ds_read_b128 v[22:25], v105 offset:8192
	ds_read_b128 v[26:29], v105 offset:8208
	ds_read_b128 v[30:33], v105 offset:16384
	ds_read_b128 v[34:37], v105 offset:16400
	ds_read_b128 v[38:41], v105 offset:24576
	ds_read_b128 v[42:45], v105 offset:24592
	ds_read_b128 v[46:49], v105 offset:32768
	ds_read_b128 v[50:53], v105 offset:32784
	ds_read_b128 v[54:57], v105 offset:40960
	ds_read_b128 v[58:61], v105 offset:40976
	ds_read_b128 v[62:65], v105 offset:49152
	ds_read_b128 v[66:69], v105 offset:49168
	ds_read_b128 v[70:73], v105 offset:57344
	ds_read_b128 v[74:77], v105 offset:57360
	ds_read_b128 v[78:81], v106
	ds_read_b128 v[82:85], v106 offset:16
	s_waitcnt vmcnt(24)
	s_waitcnt lgkmcnt(0)
	v_fmac_f32_e32 v6, v14, v86
	v_fmac_f32_e32 v7, v22, v86
	v_fmac_f32_e32 v4, v30, v86
	v_fmac_f32_e32 v5, v38, v86
	v_fmac_f32_e32 v2, v46, v86
	v_fmac_f32_e32 v3, v54, v86
	v_fmac_f32_e32 v0, v62, v86
	v_fmac_f32_e32 v1, v70, v86
	v_fmac_f32_e32 v13, v78, v86
	v_fmac_f32_e32 v6, v15, v87
	v_fmac_f32_e32 v7, v23, v87
	v_fmac_f32_e32 v4, v31, v87
	v_fmac_f32_e32 v5, v39, v87
	v_fmac_f32_e32 v2, v47, v87
	v_fmac_f32_e32 v3, v55, v87
	v_fmac_f32_e32 v0, v63, v87
	v_fmac_f32_e32 v1, v71, v87
	v_fmac_f32_e32 v13, v79, v87
	v_fmac_f32_e32 v6, v16, v88
	v_fmac_f32_e32 v7, v24, v88
	v_fmac_f32_e32 v4, v32, v88
	v_fmac_f32_e32 v5, v40, v88
	v_fmac_f32_e32 v2, v48, v88
	v_fmac_f32_e32 v3, v56, v88
	v_fmac_f32_e32 v0, v64, v88
	v_fmac_f32_e32 v1, v72, v88
	v_fmac_f32_e32 v13, v80, v88
	v_fmac_f32_e32 v6, v17, v89
	v_fmac_f32_e32 v7, v25, v89
	v_fmac_f32_e32 v4, v33, v89
	v_fmac_f32_e32 v5, v41, v89
	v_fmac_f32_e32 v2, v49, v89
	v_fmac_f32_e32 v3, v57, v89
	v_fmac_f32_e32 v0, v65, v89
	v_fmac_f32_e32 v1, v73, v89
	v_fmac_f32_e32 v13, v81, v89
	v_fmac_f32_e32 v6, v18, v90
	v_fmac_f32_e32 v7, v26, v90
	v_fmac_f32_e32 v4, v34, v90
	v_fmac_f32_e32 v5, v42, v90
	v_fmac_f32_e32 v2, v50, v90
	v_fmac_f32_e32 v3, v58, v90
	v_fmac_f32_e32 v0, v66, v90
	v_fmac_f32_e32 v1, v74, v90
	v_fmac_f32_e32 v13, v82, v90
	v_fmac_f32_e32 v6, v19, v91
	v_fmac_f32_e32 v7, v27, v91
	v_fmac_f32_e32 v4, v35, v91
	v_fmac_f32_e32 v5, v43, v91
	v_fmac_f32_e32 v2, v51, v91
	v_fmac_f32_e32 v3, v59, v91
	v_fmac_f32_e32 v0, v67, v91
	v_fmac_f32_e32 v1, v75, v91
	v_fmac_f32_e32 v13, v83, v91
	v_fmac_f32_e32 v6, v20, v92
	v_fmac_f32_e32 v7, v28, v92
	v_fmac_f32_e32 v4, v36, v92
	v_fmac_f32_e32 v5, v44, v92
	v_fmac_f32_e32 v2, v52, v92
	v_fmac_f32_e32 v3, v60, v92
	v_fmac_f32_e32 v0, v68, v92
	v_fmac_f32_e32 v1, v76, v92
	v_fmac_f32_e32 v13, v84, v92
	v_fmac_f32_e32 v6, v21, v93
	v_fmac_f32_e32 v7, v29, v93
	v_fmac_f32_e32 v4, v37, v93
	v_fmac_f32_e32 v5, v45, v93
	v_fmac_f32_e32 v2, v53, v93
	v_fmac_f32_e32 v3, v61, v93
	v_fmac_f32_e32 v0, v69, v93
	v_fmac_f32_e32 v1, v77, v93
	v_fmac_f32_e32 v13, v85, v93
	s_add_i32 s58, s58, 32
	s_cmp_eq_u32 s59, 15
	s_cbranch_scc1 .Lmod_tail_1
; #define LAS __attribute__((address_space(3)))
; __device__ __forceinline__ void prologue(const Frame& F, const Args& a) {
;     ...
;             for (int k = 0; k < 512; k += 8) {
;                 float w[8];
; #pragma unroll
;                 for (int j = 0; j < 8; ++j) w[j] = wp[(size_t)(k + j) * NMOD];
; #pragma unroll
;                 for (int r = 0; r < 9; ++r) {
;                     const f32x4 s0 = *(const LAS f32x4*)(sl + r * DM + ks * 512 + k), s1 = *(const LAS f32x4*)(sl + r * DM + ks * 512 + k + 4);
;                     acc[r] += s0[0] * w[0] + s0[1] * w[1] + s0[2] * w[2] + s0[3] * w[3] + s1[0] * w[4] + s1[1] * w[5] + s1[2] * w[6] + s1[3] * w[7];
;                 }
	global_load_dword v86, v104, s[68:69]
	s_add_u32 s68, s68, 0xc000
	s_addc_u32 s69, s69, 0
	global_load_dword v87, v104, s[68:69]
	s_add_u32 s68, s68, 0xc000
	s_addc_u32 s69, s69, 0
	global_load_dword v88, v104, s[68:69]
	s_add_u32 s68, s68, 0xc000
	s_addc_u32 s69, s69, 0
	global_load_dword v89, v104, s[68:69]
	s_add_u32 s68, s68, 0xc000
	s_addc_u32 s69, s69, 0
	global_load_dword v90, v104, s[68:69]
	s_add_u32 s68, s68, 0xc000
	s_addc_u32 s69, s69, 0
	global_load_dword v91, v104, s[68:69]
	s_add_u32 s68, s68, 0xc000
	s_addc_u32 s69, s69, 0
	global_load_dword v92, v104, s[68:69]
	s_add_u32 s68, s68, 0xc000
	s_addc_u32 s69, s69, 0
	global_load_dword v93, v104, s[68:69]
	s_add_u32 s68, s68, 0xc000
	s_addc_u32 s69, s69, 0
	v_mov_b32_e32 v105, s58
	s_add_i32 s6, s58, 0x10000
	v_mov_b32_e32 v106, s6
	ds_read_b128 v[14:17], v105
	ds_read_b128 v[18:21], v105 offset:16
	ds_read_b128 v[22:25], v105 offset:8192
	ds_read_b128 v[26:29], v105 offset:8208
	ds_read_b128 v[30:33], v105 offset:16384
	ds_read_b128 v[34:37], v105 offset:16400
	ds_read_b128 v[38:41], v105 offset:24576
	ds_read_b128 v[42:45], v105 offset:24592
	ds_read_b128 v[46:49], v105 offset:32768
	ds_read_b128 v[50:53], v105 offset:32784
	ds_read_b128 v[54:57], v105 offset:40960
	ds_read_b128 v[58:61], v105 offset:40976
	ds_read_b128 v[62:65], v105 offset:49152
	ds_read_b128 v[66:69], v105 offset:49168
	ds_read_b128 v[70:73], v105 offset:57344
	ds_read_b128 v[74:77], v105 offset:57360
	ds_read_b128 v[78:81], v106
	ds_read_b128 v[82:85], v106 offset:16
	s_waitcnt vmcnt(24)
	s_branch .Lmod_go_1
.Lmod_tail_1:
	v_mov_b32_e32 v105, s58
	s_add_i32 s6, s58, 0x10000
	v_mov_b32_e32 v106, s6
	ds_read_b128 v[14:17], v105
	ds_read_b128 v[18:21], v105 offset:16
	ds_read_b128 v[22:25], v105 offset:8192
	ds_read_b128 v[26:29], v105 offset:8208
	ds_read_b128 v[30:33], v105 offset:16384
	ds_read_b128 v[34:37], v105 offset:16400
	ds_read_b128 v[38:41], v105 offset:24576
	ds_read_b128 v[42:45], v105 offset:24592
	ds_read_b128 v[46:49], v105 offset:32768
	ds_read_b128 v[50:53], v105 offset:32784
	ds_read_b128 v[54:57], v105 offset:40960
	ds_read_b128 v[58:61], v105 offset:40976
	ds_read_b128 v[62:65], v105 offset:49152
	ds_read_b128 v[66:69], v105 offset:49168
	ds_read_b128 v[70:73], v105 offset:57344
	ds_read_b128 v[74:77], v105 offset:57360
	ds_read_b128 v[78:81], v106
	ds_read_b128 v[82:85], v106 offset:16
	s_waitcnt vmcnt(16)
.Lmod_go_1:
	s_waitcnt lgkmcnt(0)
	v_fmac_f32_e32 v6, v14, v94
	v_fmac_f32_e32 v7, v22, v94
	v_fmac_f32_e32 v4, v30, v94
	v_fmac_f32_e32 v5, v38, v94
	v_fmac_f32_e32 v2, v46, v94
	v_fmac_f32_e32 v3, v54, v94
	v_fmac_f32_e32 v0, v62, v94
	v_fmac_f32_e32 v1, v70, v94
	v_fmac_f32_e32 v13, v78, v94
	v_fmac_f32_e32 v6, v15, v95
	v_fmac_f32_e32 v7, v23, v95
	v_fmac_f32_e32 v4, v31, v95
	v_fmac_f32_e32 v5, v39, v95
	v_fmac_f32_e32 v2, v47, v95
	v_fmac_f32_e32 v3, v55, v95
	v_fmac_f32_e32 v0, v63, v95
	v_fmac_f32_e32 v1, v71, v95
	v_fmac_f32_e32 v13, v79, v95
	v_fmac_f32_e32 v6, v16, v96
	v_fmac_f32_e32 v7, v24, v96
	v_fmac_f32_e32 v4, v32, v96
	v_fmac_f32_e32 v5, v40, v96
	v_fmac_f32_e32 v2, v48, v96
	v_fmac_f32_e32 v3, v56, v96
	v_fmac_f32_e32 v0, v64, v96
	v_fmac_f32_e32 v1, v72, v96
	v_fmac_f32_e32 v13, v80, v96
	v_fmac_f32_e32 v6, v17, v97
	v_fmac_f32_e32 v7, v25, v97
	v_fmac_f32_e32 v4, v33, v97
	v_fmac_f32_e32 v5, v41, v97
	v_fmac_f32_e32 v2, v49, v97
	v_fmac_f32_e32 v3, v57, v97
	v_fmac_f32_e32 v0, v65, v97
	v_fmac_f32_e32 v1, v73, v97
	v_fmac_f32_e32 v13, v81, v97
	v_fmac_f32_e32 v6, v18, v98
	v_fmac_f32_e32 v7, v26, v98
	v_fmac_f32_e32 v4, v34, v98
	v_fmac_f32_e32 v5, v42, v98
	v_fmac_f32_e32 v2, v50, v98
	v_fmac_f32_e32 v3, v58, v98
	v_fmac_f32_e32 v0, v66, v98
	v_fmac_f32_e32 v1, v74, v98
	v_fmac_f32_e32 v13, v82, v98
	v_fmac_f32_e32 v6, v19, v99
	v_fmac_f32_e32 v7, v27, v99
	v_fmac_f32_e32 v4, v35, v99
	v_fmac_f32_e32 v5, v43, v99
	v_fmac_f32_e32 v2, v51, v99
	v_fmac_f32_e32 v3, v59, v99
	v_fmac_f32_e32 v0, v67, v99
	v_fmac_f32_e32 v1, v75, v99
	v_fmac_f32_e32 v13, v83, v99
	v_fmac_f32_e32 v6, v20, v100
	v_fmac_f32_e32 v7, v28, v100
	v_fmac_f32_e32 v4, v36, v100
	v_fmac_f32_e32 v5, v44, v100
	v_fmac_f32_e32 v2, v52, v100
	v_fmac_f32_e32 v3, v60, v100
	v_fmac_f32_e32 v0, v68, v100
	v_fmac_f32_e32 v1, v76, v100
	v_fmac_f32_e32 v13, v84, v100
	v_fmac_f32_e32 v6, v21, v101
	v_fmac_f32_e32 v7, v29, v101
	v_fmac_f32_e32 v4, v37, v101
	v_fmac_f32_e32 v5, v45, v101
	v_fmac_f32_e32 v2, v53, v101
	v_fmac_f32_e32 v3, v61, v101
	v_fmac_f32_e32 v0, v69, v101
	v_fmac_f32_e32 v1, v77, v101
	v_fmac_f32_e32 v13, v85, v101
	s_add_i32 s58, s58, 32
	s_cmp_eq_u32 s59, 15
	s_cbranch_scc1 .Lmod_tail_2
	global_load_dword v94, v104, s[68:69]
	s_add_u32 s68, s68, 0xc000
	s_addc_u32 s69, s69, 0
	global_load_dword v95, v104, s[68:69]
	s_add_u32 s68, s68, 0xc000
	s_addc_u32 s69, s69, 0
	global_load_dword v96, v104, s[68:69]
	s_add_u32 s68, s68, 0xc000
	s_addc_u32 s69, s69, 0
	global_load_dword v97, v104, s[68:69]
	s_add_u32 s68, s68, 0xc000
	s_addc_u32 s69, s69, 0
	global_load_dword v98, v104, s[68:69]
	s_add_u32 s68, s68, 0xc000
	s_addc_u32 s69, s69, 0
	global_load_dword v99, v104, s[68:69]
	s_add_u32 s68, s68, 0xc000
	s_addc_u32 s69, s69, 0
	global_load_dword v100, v104, s[68:69]
	s_add_u32 s68, s68, 0xc000
	s_addc_u32 s69, s69, 0
	global_load_dword v101, v104, s[68:69]
	s_add_u32 s68, s68, 0xc000
	s_addc_u32 s69, s69, 0
	v_mov_b32_e32 v105, s58
	s_add_i32 s6, s58, 0x10000
	v_mov_b32_e32 v106, s6
	ds_read_b128 v[14:17], v105
	ds_read_b128 v[18:21], v105 offset:16
	ds_read_b128 v[22:25], v105 offset:8192
	ds_read_b128 v[26:29], v105 offset:8208
	ds_read_b128 v[30:33], v105 offset:16384
	ds_read_b128 v[34:37], v105 offset:16400
	ds_read_b128 v[38:41], v105 offset:24576
	ds_read_b128 v[42:45], v105 offset:24592
	ds_read_b128 v[46:49], v105 offset:32768
	ds_read_b128 v[50:53], v105 offset:32784
	ds_read_b128 v[54:57], v105 offset:40960
	ds_read_b128 v[58:61], v105 offset:40976
	ds_read_b128 v[62:65], v105 offset:49152
	ds_read_b128 v[66:69], v105 offset:49168
	ds_read_b128 v[70:73], v105 offset:57344
	ds_read_b128 v[74:77], v105 offset:57360
	ds_read_b128 v[78:81], v106
	ds_read_b128 v[82:85], v106 offset:16
	s_waitcnt vmcnt(24)
	s_branch .Lmod_go_2
; #define LAS __attribute__((address_space(3)))
; __device__ __forceinline__ void prologue(const Frame& F, const Args& a) {
;     ...
;             for (int k = 0; k < 512; k += 8) {
;                 float w[8];
; #pragma unroll
;                 for (int j = 0; j < 8; ++j) w[j] = wp[(size_t)(k + j) * NMOD];
; #pragma unroll
;                 for (int r = 0; r < 9; ++r) {
;                     const f32x4 s0 = *(const LAS f32x4*)(sl + r * DM + ks * 512 + k), s1 = *(const LAS f32x4*)(sl + r * DM + ks * 512 + k + 4);
;                     acc[r] += s0[0] * w[0] + s0[1] * w[1] + s0[2] * w[2] + s0[3] * w[3] + s1[0] * w[4] + s1[1] * w[5] + s1[2] * w[6] + s1[3] * w[7];
;                 }
.Lmod_tail_2:
	v_mov_b32_e32 v105, s58
	s_add_i32 s6, s58, 0x10000
	v_mov_b32_e32 v106, s6
	ds_read_b128 v[14:17], v105
	ds_read_b128 v[18:21], v105 offset:16
	ds_read_b128 v[22:25], v105 offset:8192
	ds_read_b128 v[26:29], v105 offset:8208
	ds_read_b128 v[30:33], v105 offset:16384
	ds_read_b128 v[34:37], v105 offset:16400
	ds_read_b128 v[38:41], v105 offset:24576
	ds_read_b128 v[42:45], v105 offset:24592
	ds_read_b128 v[46:49], v105 offset:32768
	ds_read_b128 v[50:53], v105 offset:32784
	ds_read_b128 v[54:57], v105 offset:40960
	ds_read_b128 v[58:61], v105 offset:40976
	ds_read_b128 v[62:65], v105 offset:49152
	ds_read_b128 v[66:69], v105 offset:49168
	ds_read_b128 v[70:73], v105 offset:57344
	ds_read_b128 v[74:77], v105 offset:57360
	ds_read_b128 v[78:81], v106
	ds_read_b128 v[82:85], v106 offset:16
	s_waitcnt vmcnt(8)
.Lmod_go_2:
	s_waitcnt lgkmcnt(0)
	v_fmac_f32_e32 v6, v14, v107
	v_fmac_f32_e32 v7, v22, v107
	v_fmac_f32_e32 v4, v30, v107
	v_fmac_f32_e32 v5, v38, v107
	v_fmac_f32_e32 v2, v46, v107
	v_fmac_f32_e32 v3, v54, v107
	v_fmac_f32_e32 v0, v62, v107
	v_fmac_f32_e32 v1, v70, v107
	v_fmac_f32_e32 v13, v78, v107
	v_fmac_f32_e32 v6, v15, v108
	v_fmac_f32_e32 v7, v23, v108
	v_fmac_f32_e32 v4, v31, v108
	v_fmac_f32_e32 v5, v39, v108
	v_fmac_f32_e32 v2, v47, v108
	v_fmac_f32_e32 v3, v55, v108
	v_fmac_f32_e32 v0, v63, v108
	v_fmac_f32_e32 v1, v71, v108
	v_fmac_f32_e32 v13, v79, v108
	v_fmac_f32_e32 v6, v16, v109
	v_fmac_f32_e32 v7, v24, v109
	v_fmac_f32_e32 v4, v32, v109
	v_fmac_f32_e32 v5, v40, v109
	v_fmac_f32_e32 v2, v48, v109
	v_fmac_f32_e32 v3, v56, v109
	v_fmac_f32_e32 v0, v64, v109
	v_fmac_f32_e32 v1, v72, v109
	v_fmac_f32_e32 v13, v80, v109
	v_fmac_f32_e32 v6, v17, v110
	v_fmac_f32_e32 v7, v25, v110
	v_fmac_f32_e32 v4, v33, v110
	v_fmac_f32_e32 v5, v41, v110
	v_fmac_f32_e32 v2, v49, v110
	v_fmac_f32_e32 v3, v57, v110
	v_fmac_f32_e32 v0, v65, v110
	v_fmac_f32_e32 v1, v73, v110
	v_fmac_f32_e32 v13, v81, v110
	v_fmac_f32_e32 v6, v18, v111
	v_fmac_f32_e32 v7, v26, v111
	v_fmac_f32_e32 v4, v34, v111
	v_fmac_f32_e32 v5, v42, v111
	v_fmac_f32_e32 v2, v50, v111
	v_fmac_f32_e32 v3, v58, v111
	v_fmac_f32_e32 v0, v66, v111
	v_fmac_f32_e32 v1, v74, v111
	v_fmac_f32_e32 v13, v82, v111
	v_fmac_f32_e32 v6, v19, v112
	v_fmac_f32_e32 v7, v27, v112
	v_fmac_f32_e32 v4, v35, v112
	v_fmac_f32_e32 v5, v43, v112
	v_fmac_f32_e32 v2, v51, v112
	v_fmac_f32_e32 v3, v59, v112
	v_fmac_f32_e32 v0, v67, v112
	v_fmac_f32_e32 v1, v75, v112
	v_fmac_f32_e32 v13, v83, v112
	v_fmac_f32_e32 v6, v20, v113
	v_fmac_f32_e32 v7, v28, v113
	v_fmac_f32_e32 v4, v36, v113
	v_fmac_f32_e32 v5, v44, v113
	v_fmac_f32_e32 v2, v52, v113
	v_fmac_f32_e32 v3, v60, v113
	v_fmac_f32_e32 v0, v68, v113
	v_fmac_f32_e32 v1, v76, v113
	v_fmac_f32_e32 v13, v84, v113
	v_fmac_f32_e32 v6, v21, v114
	v_fmac_f32_e32 v7, v29, v114
	v_fmac_f32_e32 v4, v37, v114
	v_fmac_f32_e32 v5, v45, v114
	v_fmac_f32_e32 v2, v53, v114
	v_fmac_f32_e32 v3, v61, v114
	v_fmac_f32_e32 v0, v69, v114
	v_fmac_f32_e32 v1, v77, v114
	v_fmac_f32_e32 v13, v85, v114
	s_add_i32 s58, s58, 32
	s_cmp_eq_u32 s59, 15
	s_cbranch_scc1 .Lmod_tail_3
	global_load_dword v107, v104, s[68:69]
	s_add_u32 s68, s68, 0xc000
	s_addc_u32 s69, s69, 0
	global_load_dword v108, v104, s[68:69]
	s_add_u32 s68, s68, 0xc000
	s_addc_u32 s69, s69, 0
	global_load_dword v109, v104, s[68:69]
	s_add_u32 s68, s68, 0xc000
	s_addc_u32 s69, s69, 0
	global_load_dword v110, v104, s[68:69]
	s_add_u32 s68, s68, 0xc000
	s_addc_u32 s69, s69, 0
	global_load_dword v111, v104, s[68:69]
	s_add_u32 s68, s68, 0xc000
	s_addc_u32 s69, s69, 0
	global_load_dword v112, v104, s[68:69]
	s_add_u32 s68, s68, 0xc000
	s_addc_u32 s69, s69, 0
	global_load_dword v113, v104, s[68:69]
	s_add_u32 s68, s68, 0xc000
	s_addc_u32 s69, s69, 0
	global_load_dword v114, v104, s[68:69]
	s_add_u32 s68, s68, 0xc000
	s_addc_u32 s69, s69, 0
	v_mov_b32_e32 v105, s58
	s_add_i32 s6, s58, 0x10000
	v_mov_b32_e32 v106, s6
	ds_read_b128 v[14:17], v105
	ds_read_b128 v[18:21], v105 offset:16
	ds_read_b128 v[22:25], v105 offset:8192
	ds_read_b128 v[26:29], v105 offset:8208
	ds_read_b128 v[30:33], v105 offset:16384
	ds_read_b128 v[34:37], v105 offset:16400
	ds_read_b128 v[38:41], v105 offset:24576
	ds_read_b128 v[42:45], v105 offset:24592
	ds_read_b128 v[46:49], v105 offset:32768
	ds_read_b128 v[50:53], v105 offset:32784
	ds_read_b128 v[54:57], v105 offset:40960
	ds_read_b128 v[58:61], v105 offset:40976
	ds_read_b128 v[62:65], v105 offset:49152
	ds_read_b128 v[66:69], v105 offset:49168
	ds_read_b128 v[70:73], v105 offset:57344
	ds_read_b128 v[74:77], v105 offset:57360
	ds_read_b128 v[78:81], v106
	ds_read_b128 v[82:85], v106 offset:16
	s_waitcnt vmcnt(24)
	s_branch .Lmod_go_3
; #define LAS __attribute__((address_space(3)))
; __device__ __forceinline__ void prologue(const Frame& F, const Args& a) {
;     ...
;             for (int k = 0; k < 512; k += 8) {
;                 float w[8];
; #pragma unroll
;                 for (int j = 0; j < 8; ++j) w[j] = wp[(size_t)(k + j) * NMOD];
; #pragma unroll
;                 for (int r = 0; r < 9; ++r) {
;                     const f32x4 s0 = *(const LAS f32x4*)(sl + r * DM + ks * 512 + k), s1 = *(const LAS f32x4*)(sl + r * DM + ks * 512 + k + 4);
;                     acc[r] += s0[0] * w[0] + s0[1] * w[1] + s0[2] * w[2] + s0[3] * w[3] + s1[0] * w[4] + s1[1] * w[5] + s1[2] * w[6] + s1[3] * w[7];
;                 }
;             }
;             const float bias = (ks == 0) ? a.in[6][layer * NMOD + col] : 0.f;
.Lmod_tail_3:
	v_mov_b32_e32 v105, s58
	s_add_i32 s6, s58, 0x10000
	v_mov_b32_e32 v106, s6
	ds_read_b128 v[14:17], v105
	ds_read_b128 v[18:21], v105 offset:16
	ds_read_b128 v[22:25], v105 offset:8192
	ds_read_b128 v[26:29], v105 offset:8208
	ds_read_b128 v[30:33], v105 offset:16384
	ds_read_b128 v[34:37], v105 offset:16400
	ds_read_b128 v[38:41], v105 offset:24576
	ds_read_b128 v[42:45], v105 offset:24592
	ds_read_b128 v[46:49], v105 offset:32768
	ds_read_b128 v[50:53], v105 offset:32784
	ds_read_b128 v[54:57], v105 offset:40960
	ds_read_b128 v[58:61], v105 offset:40976
	ds_read_b128 v[62:65], v105 offset:49152
	ds_read_b128 v[66:69], v105 offset:49168
	ds_read_b128 v[70:73], v105 offset:57344
	ds_read_b128 v[74:77], v105 offset:57360
	ds_read_b128 v[78:81], v106
	ds_read_b128 v[82:85], v106 offset:16
	s_waitcnt vmcnt(0)
.Lmod_go_3:
	s_waitcnt lgkmcnt(0)
	v_fmac_f32_e32 v6, v14, v115
	v_fmac_f32_e32 v7, v22, v115
	v_fmac_f32_e32 v4, v30, v115
	v_fmac_f32_e32 v5, v38, v115
	v_fmac_f32_e32 v2, v46, v115
	v_fmac_f32_e32 v3, v54, v115
	v_fmac_f32_e32 v0, v62, v115
	v_fmac_f32_e32 v1, v70, v115
	v_fmac_f32_e32 v13, v78, v115
	v_fmac_f32_e32 v6, v15, v116
	v_fmac_f32_e32 v7, v23, v116
	v_fmac_f32_e32 v4, v31, v116
	v_fmac_f32_e32 v5, v39, v116
	v_fmac_f32_e32 v2, v47, v116
	v_fmac_f32_e32 v3, v55, v116
	v_fmac_f32_e32 v0, v63, v116
	v_fmac_f32_e32 v1, v71, v116
	v_fmac_f32_e32 v13, v79, v116
	v_fmac_f32_e32 v6, v16, v117
	v_fmac_f32_e32 v7, v24, v117
	v_fmac_f32_e32 v4, v32, v117
	v_fmac_f32_e32 v5, v40, v117
	v_fmac_f32_e32 v2, v48, v117
	v_fmac_f32_e32 v3, v56, v117
	v_fmac_f32_e32 v0, v64, v117
	v_fmac_f32_e32 v1, v72, v117
	v_fmac_f32_e32 v13, v80, v117
	v_fmac_f32_e32 v6, v17, v118
	v_fmac_f32_e32 v7, v25, v118
	v_fmac_f32_e32 v4, v33, v118
	v_fmac_f32_e32 v5, v41, v118
	v_fmac_f32_e32 v2, v49, v118
	v_fmac_f32_e32 v3, v57, v118
	v_fmac_f32_e32 v0, v65, v118
	v_fmac_f32_e32 v1, v73, v118
	v_fmac_f32_e32 v13, v81, v118
	v_fmac_f32_e32 v6, v18, v119
	v_fmac_f32_e32 v7, v26, v119
	v_fmac_f32_e32 v4, v34, v119
	v_fmac_f32_e32 v5, v42, v119
	v_fmac_f32_e32 v2, v50, v119
	v_fmac_f32_e32 v3, v58, v119
	v_fmac_f32_e32 v0, v66, v119
	v_fmac_f32_e32 v1, v74, v119
	v_fmac_f32_e32 v13, v82, v119
	v_fmac_f32_e32 v6, v19, v120
	v_fmac_f32_e32 v7, v27, v120
	v_fmac_f32_e32 v4, v35, v120
	v_fmac_f32_e32 v5, v43, v120
	v_fmac_f32_e32 v2, v51, v120
	v_fmac_f32_e32 v3, v59, v120
	v_fmac_f32_e32 v0, v67, v120
	v_fmac_f32_e32 v1, v75, v120
	v_fmac_f32_e32 v13, v83, v120
	v_fmac_f32_e32 v6, v20, v121
	v_fmac_f32_e32 v7, v28, v121
	v_fmac_f32_e32 v4, v36, v121
	v_fmac_f32_e32 v5, v44, v121
	v_fmac_f32_e32 v2, v52, v121
	v_fmac_f32_e32 v3, v60, v121
	v_fmac_f32_e32 v0, v68, v121
	v_fmac_f32_e32 v1, v76, v121
	v_fmac_f32_e32 v13, v84, v121
	v_fmac_f32_e32 v6, v21, v122
	v_fmac_f32_e32 v7, v29, v122
	v_fmac_f32_e32 v4, v37, v122
	v_fmac_f32_e32 v5, v45, v122
	v_fmac_f32_e32 v2, v53, v122
	v_fmac_f32_e32 v3, v61, v122
	v_fmac_f32_e32 v0, v69, v122
	v_fmac_f32_e32 v1, v77, v122
	v_fmac_f32_e32 v13, v85, v122
	s_add_i32 s58, s58, 32
	s_add_i32 s59, s59, 1
	s_cmp_lt_u32 s59, 16
	s_cbranch_scc1 .LBB0_26
	s_cmp_lg_u32 s55, 0
	v_mov_b32_e32 v10, 0
	s_cbranch_scc1 .LBB0_24
	s_mul_i32 s6, s54, 0x3000
	v_add_u32_e32 v10, s6, v8
	v_ashrrev_i32_e32 v11, 31, v10
	v_lshl_add_u64 v[10:11], v[10:11], 2, s[64:65]
	global_load_dword v10, v[10:11], off
	s_branch .LBB0_24

; __device__ __forceinline__ void transpose_item(const float* __restrict__ W, int K, int N, int NV, bf16_t* __restrict__ WT, LAS float* scr, int item, int nblk, int lane, int mode, const float* __restrict__ kscale) {
;     const int kb = item / nblk, nb = item % nblk, k0 = 64 * kb, n0 = 32 * nb;
;     const int nd = n0 + (lane & 31); const bool valid = nd < NV; const int ns = valid ? srccol(mode, nd) : 0;
; #pragma unroll 8
;     for (int i = 0; i < 32; ++i) { const int kk = 2 * i + (lane >> 5); float v = valid ? W[(size_t)(k0 + kk) * N + ns] : 0.f; if (kscale) v *= kscale[k0 + kk]; scr[kk * 33 + (lane & 31)] = v; }
.LBB0_56:
	s_lshl_b32 s6, s59, 1
	s_lshl_b32 s7, s62, 1
	v_or_b32_e32 v61, s7, v0
	s_add_i32 s34, s6, 4
	s_add_i32 s35, s7, 4
	s_add_i32 s83, s7, 8
	v_add_u32_e32 v6, s10, v61
	v_or_b32_e32 v62, s34, v1
	v_or_b32_e32 v63, s35, v0
	v_mov_b32_e32 v27, v7
	v_or_b32_e32 v60, s6, v1
	s_add_i32 s87, s7, 12
	v_or_b32_e32 v65, s83, v0
	v_lshlrev_b64 v[40:41], 13, v[6:7]
	v_add_u32_e32 v26, s58, v62
	v_add_u32_e32 v6, s10, v63
	v_mov_b32_e32 v25, v7
	s_add_i32 s82, s6, 8
	s_add_i32 s86, s6, 12
	s_add_i32 s89, s7, 16
	v_add_u32_e32 v24, s58, v60
	v_or_b32_e32 v67, s87, v0
	v_lshlrev_b64 v[26:27], 13, v[26:27]
	v_lshlrev_b64 v[56:57], 13, v[6:7]
	v_add_u32_e32 v6, s10, v65
	s_add_i32 s91, s7, 20
	v_or_b32_e32 v64, s82, v1
	v_or_b32_e32 v66, s86, v1
	v_or_b32_e32 v69, s89, v0
	v_lshlrev_b64 v[24:25], 13, v[24:25]
	v_lshl_add_u64 v[40:41], v[22:23], 0, v[40:41]
	v_lshl_add_u64 v[26:27], v[22:23], 0, v[26:27]
	v_lshlrev_b64 v[58:59], 13, v[6:7]
	v_add_u32_e32 v6, s10, v67
	v_mov_b32_e32 v29, v7
	v_mov_b32_e32 v31, v7
	s_add_i32 s88, s6, 16
	s_add_i32 s90, s6, 20
	s_add_i32 s93, s7, 24
	v_or_b32_e32 v71, s91, v0
	v_add_u32_e32 v28, s58, v64
	v_add_u32_e32 v30, s58, v66
	v_lshl_add_u64 v[24:25], v[22:23], 0, v[24:25]
	v_lshl_add_u64 v[56:57], v[22:23], 0, v[56:57]
	global_load_dword v76, v[40:41], off
	global_load_dword v77, v[24:25], off
	global_load_dword v78, v[56:57], off
	global_load_dword v79, v[26:27], off
	v_lshlrev_b64 v[26:27], 13, v[6:7]
	v_add_u32_e32 v6, s10, v69
	s_add_i32 s92, s6, 24
	s_add_i32 s6, s6, 28
	s_add_i32 s7, s7, 28
	v_or_b32_e32 v68, s88, v1
	v_or_b32_e32 v70, s90, v1
	v_or_b32_e32 v73, s93, v0
	v_lshlrev_b64 v[28:29], 13, v[28:29]
	v_lshlrev_b64 v[30:31], 13, v[30:31]
	v_lshl_add_u64 v[24:25], v[22:23], 0, v[58:59]
	v_lshl_add_u64 v[26:27], v[22:23], 0, v[26:27]
	v_lshlrev_b64 v[40:41], 13, v[6:7]
	v_add_u32_e32 v6, s10, v71
	v_mov_b32_e32 v33, v7
	v_mov_b32_e32 v35, v7
	v_or_b32_e32 v72, s92, v1
	v_or_b32_e32 v74, s6, v1
	v_or_b32_e32 v75, s7, v0
	v_add_u32_e32 v32, s58, v68
	v_add_u32_e32 v34, s58, v70
	v_lshl_add_u64 v[28:29], v[22:23], 0, v[28:29]
	v_lshl_add_u64 v[30:31], v[22:23], 0, v[30:31]
	global_load_dword v80, v[24:25], off
	global_load_dword v81, v[28:29], off
	global_load_dword v82, v[26:27], off
	global_load_dword v83, v[30:31], off
	v_lshlrev_b64 v[26:27], 13, v[6:7]
	v_add_u32_e32 v6, s10, v73
	v_mov_b32_e32 v37, v7
	v_mov_b32_e32 v39, v7
	v_add_u32_e32 v36, s58, v72
	v_add_u32_e32 v38, s58, v74
	v_lshlrev_b64 v[32:33], 13, v[32:33]
	v_lshlrev_b64 v[34:35], 13, v[34:35]
	v_lshl_add_u64 v[24:25], v[22:23], 0, v[40:41]
	v_lshl_add_u64 v[26:27], v[22:23], 0, v[26:27]
	v_lshlrev_b64 v[28:29], 13, v[6:7]
	v_add_u32_e32 v6, s10, v75
	v_lshlrev_b64 v[36:37], 13, v[36:37]
	v_lshlrev_b64 v[38:39], 13, v[38:39]
	v_lshl_add_u64 v[32:33], v[22:23], 0, v[32:33]
	v_lshl_add_u64 v[34:35], v[22:23], 0, v[34:35]
	global_load_dword v84, v[24:25], off
	global_load_dword v85, v[32:33], off
	global_load_dword v86, v[26:27], off
	global_load_dword v87, v[34:35], off
	v_lshl_add_u64 v[24:25], v[22:23], 0, v[28:29]
	v_lshlrev_b64 v[26:27], 13, v[6:7]
	v_lshl_add_u64 v[36:37], v[22:23], 0, v[36:37]
	v_lshl_add_u64 v[38:39], v[22:23], 0, v[38:39]
	v_lshl_add_u64 v[26:27], v[22:23], 0, v[26:27]
	global_load_dword v6, v[24:25], off
	global_load_dword v88, v[36:37], off
	global_load_dword v89, v[26:27], off
	global_load_dword v90, v[38:39], off
	s_add_i32 s62, s62, 16
	s_add_i32 s59, s59, 16
	s_add_i32 s63, s63, -16
	v_mov_b32_e32 v117, v7
	s_lshl_b32 s6, s59, 1
	s_lshl_b32 s7, s62, 1
	v_or_b32_e32 v171, s7, v0
	s_add_i32 s34, s6, 4
	s_add_i32 s35, s7, 4
	s_add_i32 s83, s7, 8
	v_add_u32_e32 v116, s10, v171
	v_or_b32_e32 v172, s34, v1
	v_or_b32_e32 v173, s35, v0
	v_mov_b32_e32 v137, v7
	v_or_b32_e32 v170, s6, v1
	s_add_i32 s87, s7, 12
	v_or_b32_e32 v175, s83, v0
	v_lshlrev_b64 v[150:151], 13, v[116:117]
	v_add_u32_e32 v136, s58, v172
	v_add_u32_e32 v116, s10, v173
	v_mov_b32_e32 v135, v7
	s_add_i32 s82, s6, 8
	s_add_i32 s86, s6, 12
	s_add_i32 s89, s7, 16
	v_add_u32_e32 v134, s58, v170
	v_or_b32_e32 v177, s87, v0
	v_lshlrev_b64 v[136:137], 13, v[136:137]
	v_lshlrev_b64 v[166:167], 13, v[116:117]
	v_add_u32_e32 v116, s10, v175
	s_add_i32 s91, s7, 20
	v_or_b32_e32 v174, s82, v1
	v_or_b32_e32 v176, s86, v1
	v_or_b32_e32 v179, s89, v0
	v_lshlrev_b64 v[134:135], 13, v[134:135]
	v_lshl_add_u64 v[150:151], v[22:23], 0, v[150:151]
	v_lshl_add_u64 v[136:137], v[22:23], 0, v[136:137]
	v_lshlrev_b64 v[168:169], 13, v[116:117]
	v_add_u32_e32 v116, s10, v177
	v_mov_b32_e32 v139, v7
	v_mov_b32_e32 v141, v7
	s_add_i32 s88, s6, 16
	s_add_i32 s90, s6, 20
	s_add_i32 s93, s7, 24
	v_or_b32_e32 v181, s91, v0
	v_add_u32_e32 v138, s58, v174
	v_add_u32_e32 v140, s58, v176
	v_lshl_add_u64 v[134:135], v[22:23], 0, v[134:135]
	v_lshl_add_u64 v[166:167], v[22:23], 0, v[166:167]
	global_load_dword v186, v[150:151], off
	global_load_dword v187, v[134:135], off
	global_load_dword v188, v[166:167], off
	global_load_dword v189, v[136:137], off
	v_lshlrev_b64 v[136:137], 13, v[116:117]
	v_add_u32_e32 v116, s10, v179
	s_add_i32 s92, s6, 24
	s_add_i32 s6, s6, 28
	s_add_i32 s7, s7, 28
	v_or_b32_e32 v178, s88, v1
	v_or_b32_e32 v180, s90, v1
	v_or_b32_e32 v183, s93, v0
	v_lshlrev_b64 v[138:139], 13, v[138:139]
	v_lshlrev_b64 v[140:141], 13, v[140:141]
	v_lshl_add_u64 v[134:135], v[22:23], 0, v[168:169]
	v_lshl_add_u64 v[136:137], v[22:23], 0, v[136:137]
	v_lshlrev_b64 v[150:151], 13, v[116:117]
	v_add_u32_e32 v116, s10, v181
	v_mov_b32_e32 v143, v7
	v_mov_b32_e32 v145, v7
	v_or_b32_e32 v182, s92, v1
	v_or_b32_e32 v184, s6, v1
	v_or_b32_e32 v185, s7, v0
	v_add_u32_e32 v142, s58, v178
; __device__ __forceinline__ void transpose_item(const float* __restrict__ W, int K, int N, int NV, bf16_t* __restrict__ WT, LAS float* scr, int item, int nblk, int lane, int mode, const float* __restrict__ kscale) {
;     ...
;     for (int i = 0; i < 32; ++i) { const int kk = 2 * i + (lane >> 5); float v = valid ? W[(size_t)(k0 + kk) * N + ns] : 0.f; if (kscale) v *= kscale[k0 + kk]; scr[kk * 33 + (lane & 31)] = v; }
	v_add_u32_e32 v144, s58, v180
	v_lshl_add_u64 v[138:139], v[22:23], 0, v[138:139]
	v_lshl_add_u64 v[140:141], v[22:23], 0, v[140:141]
	global_load_dword v190, v[134:135], off
	global_load_dword v191, v[138:139], off
	global_load_dword v192, v[136:137], off
	global_load_dword v193, v[140:141], off
	v_lshlrev_b64 v[136:137], 13, v[116:117]
	v_add_u32_e32 v116, s10, v183
	v_mov_b32_e32 v147, v7
	v_mov_b32_e32 v149, v7
	v_add_u32_e32 v146, s58, v182
	v_add_u32_e32 v148, s58, v184
	v_lshlrev_b64 v[142:143], 13, v[142:143]
	v_lshlrev_b64 v[144:145], 13, v[144:145]
	v_lshl_add_u64 v[134:135], v[22:23], 0, v[150:151]
	v_lshl_add_u64 v[136:137], v[22:23], 0, v[136:137]
	v_lshlrev_b64 v[138:139], 13, v[116:117]
	v_add_u32_e32 v116, s10, v185
	v_lshlrev_b64 v[146:147], 13, v[146:147]
	v_lshlrev_b64 v[148:149], 13, v[148:149]
	v_lshl_add_u64 v[142:143], v[22:23], 0, v[142:143]
	v_lshl_add_u64 v[144:145], v[22:23], 0, v[144:145]
	global_load_dword v194, v[134:135], off
	global_load_dword v195, v[142:143], off
	global_load_dword v196, v[136:137], off
	global_load_dword v197, v[144:145], off
	v_lshl_add_u64 v[134:135], v[22:23], 0, v[138:139]
	v_lshlrev_b64 v[136:137], 13, v[116:117]
	v_lshl_add_u64 v[146:147], v[22:23], 0, v[146:147]
	v_lshl_add_u64 v[148:149], v[22:23], 0, v[148:149]
	v_lshl_add_u64 v[136:137], v[22:23], 0, v[136:137]
	global_load_dword v116, v[134:135], off
	global_load_dword v198, v[146:147], off
	global_load_dword v199, v[136:137], off
	global_load_dword v200, v[148:149], off
	s_add_i32 s62, s62, 16
	s_add_i32 s59, s59, 16
	s_add_i32 s63, s63, -16
	v_mad_u64_u32 v[24:25], s[82:83], v61, s70, v[2:3]
	v_mad_u64_u32 v[26:27], s[82:83], v60, s70, v[2:3]
	v_mad_u64_u32 v[28:29], s[82:83], v63, s70, v[2:3]
	v_mad_u64_u32 v[30:31], s[82:83], v62, s70, v[2:3]
	v_mad_u64_u32 v[32:33], s[82:83], v65, s70, v[2:3]
	v_mad_u64_u32 v[34:35], s[82:83], v64, s70, v[2:3]
	v_mad_u64_u32 v[36:37], s[82:83], v67, s70, v[2:3]
	v_mad_u64_u32 v[38:39], s[82:83], v66, s70, v[2:3]
	v_mad_u64_u32 v[40:41], s[82:83], v69, s70, v[2:3]
	v_mad_u64_u32 v[56:57], s[82:83], v68, s70, v[2:3]
	v_mad_u64_u32 v[58:59], s[82:83], v71, s70, v[2:3]
	v_mad_u64_u32 v[60:61], s[82:83], v70, s70, v[2:3]
	v_mad_u64_u32 v[62:63], s[82:83], v73, s70, v[2:3]
	v_mad_u64_u32 v[64:65], s[82:83], v72, s70, v[2:3]
	v_mad_u64_u32 v[66:67], s[82:83], v75, s70, v[2:3]
	v_mad_u64_u32 v[68:69], s[82:83], v74, s70, v[2:3]
	s_waitcnt vmcnt(31)
	ds_write_b32 v24, v76
	s_waitcnt vmcnt(30)
	ds_write_b32 v26, v77
	s_waitcnt vmcnt(29)
	ds_write_b32 v28, v78
	s_waitcnt vmcnt(28)
	ds_write_b32 v30, v79
	s_waitcnt vmcnt(27)
	ds_write_b32 v32, v80
	s_waitcnt vmcnt(26)
	ds_write_b32 v34, v81
	s_waitcnt vmcnt(25)
	ds_write_b32 v36, v82
	s_waitcnt vmcnt(24)
	ds_write_b32 v38, v83
	s_waitcnt vmcnt(23)
	ds_write_b32 v40, v84
	s_waitcnt vmcnt(22)
	ds_write_b32 v56, v85
	s_waitcnt vmcnt(21)
	ds_write_b32 v58, v86
	s_waitcnt vmcnt(20)
	ds_write_b32 v60, v87
	s_waitcnt vmcnt(19)
	ds_write_b32 v62, v6
	s_waitcnt vmcnt(18)
	ds_write_b32 v64, v88
	s_waitcnt vmcnt(17)
	ds_write_b32 v66, v89
	s_waitcnt vmcnt(16)
	ds_write_b32 v68, v90
	v_mad_u64_u32 v[134:135], s[82:83], v171, s70, v[2:3]
	v_mad_u64_u32 v[136:137], s[82:83], v170, s70, v[2:3]
	v_mad_u64_u32 v[138:139], s[82:83], v173, s70, v[2:3]
	v_mad_u64_u32 v[140:141], s[82:83], v172, s70, v[2:3]
	v_mad_u64_u32 v[142:143], s[82:83], v175, s70, v[2:3]
	v_mad_u64_u32 v[144:145], s[82:83], v174, s70, v[2:3]
	v_mad_u64_u32 v[146:147], s[82:83], v177, s70, v[2:3]
	v_mad_u64_u32 v[148:149], s[82:83], v176, s70, v[2:3]
	v_mad_u64_u32 v[150:151], s[82:83], v179, s70, v[2:3]
	v_mad_u64_u32 v[166:167], s[82:83], v178, s70, v[2:3]
	v_mad_u64_u32 v[168:169], s[82:83], v181, s70, v[2:3]
	v_mad_u64_u32 v[170:171], s[82:83], v180, s70, v[2:3]
	v_mad_u64_u32 v[172:173], s[82:83], v183, s70, v[2:3]
	v_mad_u64_u32 v[174:175], s[82:83], v182, s70, v[2:3]
	v_mad_u64_u32 v[176:177], s[82:83], v185, s70, v[2:3]
	v_mad_u64_u32 v[178:179], s[82:83], v184, s70, v[2:3]
	s_waitcnt vmcnt(15)
; #define LAS __attribute__((address_space(3)))
; __device__ __forceinline__ unsigned pk_bf16(float lo, float hi) { f32x2 v = {lo, hi}; bf16x2_t b = __builtin_convertvector(v, bf16x2_t); return __builtin_bit_cast(unsigned, b); }
; __device__ __forceinline__ void transpose_item(const float* __restrict__ W, int K, int N, int NV, bf16_t* __restrict__ WT, LAS float* scr, int item, int nblk, int lane, int mode, const float* __restrict__ kscale) {
;     ...
;     for (int i = 0; i < 32; ++i) { const int kk = 2 * i + (lane >> 5); float v = valid ? W[(size_t)(k0 + kk) * N + ns] : 0.f; if (kscale) v *= kscale[k0 + kk]; scr[kk * 33 + (lane & 31)] = v; }
;     asm volatile("s_waitcnt lgkmcnt(0)" ::: "memory");
;     const int c = lane & 7;
; #pragma unroll
;     for (int j = 0; j < 4; ++j) { const int n = (lane >> 3) + 8 * j; const LAS float* s = scr + (8 * c) * 33 + n;
;         u32x4 o; o.x = pk_bf16(s[0 * 33], s[1 * 33]); o.y = pk_bf16(s[2 * 33], s[3 * 33]); o.z = pk_bf16(s[4 * 33], s[5 * 33]); o.w = pk_bf16(s[6 * 33], s[7 * 33]);
;         *(u32x4*)(WT + (size_t)(n0 + n) * K + k0 + 8 * c) = o; }
;     asm volatile("s_waitcnt lgkmcnt(0)" ::: "memory");
	ds_write_b32 v134, v186
	s_waitcnt vmcnt(14)
	ds_write_b32 v136, v187
	s_waitcnt vmcnt(13)
	ds_write_b32 v138, v188
	s_waitcnt vmcnt(12)
	ds_write_b32 v140, v189
	s_waitcnt vmcnt(11)
	ds_write_b32 v142, v190
	s_waitcnt vmcnt(10)
	ds_write_b32 v144, v191
	s_waitcnt vmcnt(9)
	ds_write_b32 v146, v192
	s_waitcnt vmcnt(8)
	ds_write_b32 v148, v193
	s_waitcnt vmcnt(7)
	ds_write_b32 v150, v194
	s_waitcnt vmcnt(6)
	ds_write_b32 v166, v195
	s_waitcnt vmcnt(5)
	ds_write_b32 v168, v196
	s_waitcnt vmcnt(4)
	ds_write_b32 v170, v197
	s_waitcnt vmcnt(3)
	ds_write_b32 v172, v116
	s_waitcnt vmcnt(2)
	ds_write_b32 v174, v198
	s_waitcnt vmcnt(1)
	ds_write_b32 v176, v199
	s_waitcnt vmcnt(0)
	ds_write_b32 v178, v200
	s_lshl_b64 s[0:1], s[0:1], 1
	s_add_u32 s0, s64, s0
	s_waitcnt lgkmcnt(0)
	s_addc_u32 s1, s65, s1
	s_lshl_b32 s6, s10, 1
	ds_read2_b32 v[26:27], v42 offset0:33 offset1:41
	ds_read2_b32 v[28:29], v42 offset1:8
	ds_read2_b32 v[30:31], v42 offset0:66 offset1:74
	ds_read2_b32 v[32:33], v42 offset0:99 offset1:107
	ds_read2_b32 v[34:35], v42 offset0:132 offset1:140
	ds_read2_b32 v[36:37], v42 offset0:165 offset1:173
	ds_read2_b32 v[38:39], v42 offset0:198 offset1:206
	ds_read2_b32 v[40:41], v42 offset0:231 offset1:239
	s_add_u32 s0, s0, s6
	s_addc_u32 s1, s1, 0
	v_lshlrev_b32_e32 v6, 1, v4
	v_lshl_add_u64 v[56:57], s[0:1], 0, v[6:7]
	v_or_b32_e32 v6, s9, v21
	v_lshlrev_b32_e32 v6, 14, v6
	s_waitcnt lgkmcnt(6)
	v_cvt_pk_bf16_f32 v22, v28, v26
	s_waitcnt lgkmcnt(4)
	v_cvt_pk_bf16_f32 v23, v30, v32
	s_waitcnt lgkmcnt(2)
	v_cvt_pk_bf16_f32 v24, v34, v36
	s_waitcnt lgkmcnt(0)
	v_cvt_pk_bf16_f32 v25, v38, v40
	v_lshl_add_u64 v[58:59], v[56:57], 0, v[6:7]
	global_store_dwordx4 v[58:59], v[22:25], off
	v_or_b32_e32 v6, s9, v43
	v_lshlrev_b32_e32 v6, 14, v6
	v_cvt_pk_bf16_f32 v22, v29, v27
	v_cvt_pk_bf16_f32 v23, v31, v33
	v_cvt_pk_bf16_f32 v24, v35, v37
	v_cvt_pk_bf16_f32 v25, v39, v41
	ds_read2_b32 v[28:29], v42 offset0:49 offset1:57
	ds_read2_b32 v[30:31], v42 offset0:16 offset1:24
	ds_read2_b32 v[32:33], v42 offset0:82 offset1:90
	ds_read2_b32 v[34:35], v42 offset0:115 offset1:123
	ds_read2_b32 v[36:37], v42 offset0:148 offset1:156
	ds_read2_b32 v[38:39], v42 offset0:181 offset1:189
	ds_read2_b32 v[40:41], v42 offset0:214 offset1:222
	ds_read2_b32 v[58:59], v42 offset0:247 offset1:255
	v_lshl_add_u64 v[26:27], v[56:57], 0, v[6:7]
	v_or_b32_e32 v6, s9, v44
	v_lshlrev_b32_e32 v6, 14, v6
	global_store_dwordx4 v[26:27], v[22:25], off
	v_lshl_add_u64 v[26:27], v[56:57], 0, v[6:7]
	v_or_b32_e32 v6, s9, v45
	s_waitcnt lgkmcnt(6)
	v_cvt_pk_bf16_f32 v22, v30, v28
	s_waitcnt lgkmcnt(4)
	v_cvt_pk_bf16_f32 v23, v32, v34
	s_waitcnt lgkmcnt(2)
	v_cvt_pk_bf16_f32 v24, v36, v38
	s_waitcnt lgkmcnt(0)
	v_cvt_pk_bf16_f32 v25, v40, v58
	v_lshlrev_b32_e32 v6, 14, v6
	global_store_dwordx4 v[26:27], v[22:25], off
	v_lshl_add_u64 v[26:27], v[56:57], 0, v[6:7]
	v_readlane_b32 s92, v242, 2
	v_cvt_pk_bf16_f32 v22, v31, v29
	v_cvt_pk_bf16_f32 v23, v33, v35
	v_cvt_pk_bf16_f32 v24, v37, v39
	v_cvt_pk_bf16_f32 v25, v41, v59
	global_store_dwordx4 v[26:27], v[22:25], off
	s_waitcnt lgkmcnt(0)
	v_readlane_b32 s88, v242, 4
	s_mov_b64 s[0:1], 0
	v_readlane_b32 s84, v242, 1
	v_readlane_b32 s93, v242, 3
	v_readlane_b32 s89, v242, 5

; __device__ __forceinline__ void transpose_item(const float* __restrict__ W, int K, int N, int NV, bf16_t* __restrict__ WT, LAS float* scr, int item, int nblk, int lane, int mode, const float* __restrict__ kscale) {
;     const int kb = item / nblk, nb = item % nblk, k0 = 64 * kb, n0 = 32 * nb;
;     const int nd = n0 + (lane & 31); const bool valid = nd < NV; const int ns = valid ? srccol(mode, nd) : 0;
; #pragma unroll 8
;     for (int i = 0; i < 32; ++i) { const int kk = 2 * i + (lane >> 5); float v = valid ? W[(size_t)(k0 + kk) * N + ns] : 0.f; if (kscale) v *= kscale[k0 + kk]; scr[kk * 33 + (lane & 31)] = v; }
.LBB0_60:
	s_lshl_b32 s6, s59, 1
	s_lshl_b32 s7, s62, 1
	v_or_b32_e32 v61, s7, v0
	s_add_i32 s34, s6, 4
	s_add_i32 s35, s7, 4
	s_add_i32 s83, s7, 8
	v_add_u32_e32 v6, s10, v61
	v_or_b32_e32 v62, s34, v1
	v_or_b32_e32 v63, s35, v0
	v_mov_b32_e32 v27, v7
	v_or_b32_e32 v60, s6, v1
	s_add_i32 s87, s7, 12
	v_or_b32_e32 v65, s83, v0
	v_lshlrev_b64 v[40:41], 15, v[6:7]
	v_add_u32_e32 v26, s58, v62
	v_add_u32_e32 v6, s10, v63
	v_mov_b32_e32 v25, v7
	s_add_i32 s82, s6, 8
	s_add_i32 s86, s6, 12
	s_add_i32 s89, s7, 16
	v_add_u32_e32 v24, s58, v60
	v_or_b32_e32 v67, s87, v0
	v_lshlrev_b64 v[26:27], 15, v[26:27]
	v_lshlrev_b64 v[56:57], 15, v[6:7]
	v_add_u32_e32 v6, s10, v65
	s_add_i32 s91, s7, 20
	v_or_b32_e32 v64, s82, v1
	v_or_b32_e32 v66, s86, v1
	v_or_b32_e32 v69, s89, v0
	v_lshlrev_b64 v[24:25], 15, v[24:25]
	v_lshl_add_u64 v[40:41], v[22:23], 0, v[40:41]
	v_lshl_add_u64 v[26:27], v[22:23], 0, v[26:27]
	v_lshlrev_b64 v[58:59], 15, v[6:7]
	v_add_u32_e32 v6, s10, v67
	v_mov_b32_e32 v29, v7
	v_mov_b32_e32 v31, v7
	s_add_i32 s88, s6, 16
	s_add_i32 s90, s6, 20
	s_add_i32 s93, s7, 24
	v_or_b32_e32 v71, s91, v0
	v_add_u32_e32 v28, s58, v64
	v_add_u32_e32 v30, s58, v66
	v_lshl_add_u64 v[24:25], v[22:23], 0, v[24:25]
	v_lshl_add_u64 v[56:57], v[22:23], 0, v[56:57]
	global_load_dword v76, v[40:41], off
	global_load_dword v77, v[24:25], off
	global_load_dword v78, v[56:57], off
	global_load_dword v79, v[26:27], off
	v_lshlrev_b64 v[26:27], 15, v[6:7]
	v_add_u32_e32 v6, s10, v69
	s_add_i32 s92, s6, 24
	s_add_i32 s6, s6, 28
	s_add_i32 s7, s7, 28
	v_or_b32_e32 v68, s88, v1
	v_or_b32_e32 v70, s90, v1
	v_or_b32_e32 v73, s93, v0
	v_lshlrev_b64 v[28:29], 15, v[28:29]
	v_lshlrev_b64 v[30:31], 15, v[30:31]
	v_lshl_add_u64 v[24:25], v[22:23], 0, v[58:59]
	v_lshl_add_u64 v[26:27], v[22:23], 0, v[26:27]
	v_lshlrev_b64 v[40:41], 15, v[6:7]
	v_add_u32_e32 v6, s10, v71
	v_mov_b32_e32 v33, v7
	v_mov_b32_e32 v35, v7
	v_or_b32_e32 v72, s92, v1
	v_or_b32_e32 v74, s6, v1
	v_or_b32_e32 v75, s7, v0
	v_add_u32_e32 v32, s58, v68
	v_add_u32_e32 v34, s58, v70
	v_lshl_add_u64 v[28:29], v[22:23], 0, v[28:29]
	v_lshl_add_u64 v[30:31], v[22:23], 0, v[30:31]
	global_load_dword v80, v[24:25], off
	global_load_dword v81, v[28:29], off
	global_load_dword v82, v[26:27], off
	global_load_dword v83, v[30:31], off
	v_lshlrev_b64 v[26:27], 15, v[6:7]
	v_add_u32_e32 v6, s10, v73
	v_mov_b32_e32 v37, v7
	v_mov_b32_e32 v39, v7
	v_add_u32_e32 v36, s58, v72
	v_add_u32_e32 v38, s58, v74
	v_lshlrev_b64 v[32:33], 15, v[32:33]
	v_lshlrev_b64 v[34:35], 15, v[34:35]
	v_lshl_add_u64 v[24:25], v[22:23], 0, v[40:41]
	v_lshl_add_u64 v[26:27], v[22:23], 0, v[26:27]
	v_lshlrev_b64 v[28:29], 15, v[6:7]
	v_add_u32_e32 v6, s10, v75
	v_lshlrev_b64 v[36:37], 15, v[36:37]
	v_lshlrev_b64 v[38:39], 15, v[38:39]
	v_lshl_add_u64 v[32:33], v[22:23], 0, v[32:33]
	v_lshl_add_u64 v[34:35], v[22:23], 0, v[34:35]
	global_load_dword v84, v[24:25], off
	global_load_dword v85, v[32:33], off
	global_load_dword v86, v[26:27], off
	global_load_dword v87, v[34:35], off
	v_lshl_add_u64 v[24:25], v[22:23], 0, v[28:29]
	v_lshlrev_b64 v[26:27], 15, v[6:7]
	v_lshl_add_u64 v[36:37], v[22:23], 0, v[36:37]
	v_lshl_add_u64 v[38:39], v[22:23], 0, v[38:39]
	v_lshl_add_u64 v[26:27], v[22:23], 0, v[26:27]
	global_load_dword v6, v[24:25], off
	global_load_dword v88, v[36:37], off
	global_load_dword v89, v[26:27], off
	global_load_dword v90, v[38:39], off
	s_add_i32 s62, s62, 16
	s_add_i32 s59, s59, 16
	s_add_i32 s63, s63, -16
	v_mov_b32_e32 v117, v7
	s_lshl_b32 s6, s59, 1
	s_lshl_b32 s7, s62, 1
	v_or_b32_e32 v171, s7, v0
	s_add_i32 s34, s6, 4
	s_add_i32 s35, s7, 4
	s_add_i32 s83, s7, 8
	v_add_u32_e32 v116, s10, v171
	v_or_b32_e32 v172, s34, v1
	v_or_b32_e32 v173, s35, v0
	v_mov_b32_e32 v137, v7
	v_or_b32_e32 v170, s6, v1
	s_add_i32 s87, s7, 12
	v_or_b32_e32 v175, s83, v0
	v_lshlrev_b64 v[150:151], 15, v[116:117]
	v_add_u32_e32 v136, s58, v172
	v_add_u32_e32 v116, s10, v173
	v_mov_b32_e32 v135, v7
	s_add_i32 s82, s6, 8
	s_add_i32 s86, s6, 12
	s_add_i32 s89, s7, 16
	v_add_u32_e32 v134, s58, v170
	v_or_b32_e32 v177, s87, v0
	v_lshlrev_b64 v[136:137], 15, v[136:137]
	v_lshlrev_b64 v[166:167], 15, v[116:117]
	v_add_u32_e32 v116, s10, v175
	s_add_i32 s91, s7, 20
	v_or_b32_e32 v174, s82, v1
	v_or_b32_e32 v176, s86, v1
	v_or_b32_e32 v179, s89, v0
	v_lshlrev_b64 v[134:135], 15, v[134:135]
	v_lshl_add_u64 v[150:151], v[22:23], 0, v[150:151]
	v_lshl_add_u64 v[136:137], v[22:23], 0, v[136:137]
	v_lshlrev_b64 v[168:169], 15, v[116:117]
	v_add_u32_e32 v116, s10, v177
	v_mov_b32_e32 v139, v7
	v_mov_b32_e32 v141, v7
	s_add_i32 s88, s6, 16
	s_add_i32 s90, s6, 20
	s_add_i32 s93, s7, 24
	v_or_b32_e32 v181, s91, v0
	v_add_u32_e32 v138, s58, v174
	v_add_u32_e32 v140, s58, v176
	v_lshl_add_u64 v[134:135], v[22:23], 0, v[134:135]
	v_lshl_add_u64 v[166:167], v[22:23], 0, v[166:167]
	global_load_dword v186, v[150:151], off
	global_load_dword v187, v[134:135], off
	global_load_dword v188, v[166:167], off
	global_load_dword v189, v[136:137], off
	v_lshlrev_b64 v[136:137], 15, v[116:117]
	v_add_u32_e32 v116, s10, v179
	s_add_i32 s92, s6, 24
	s_add_i32 s6, s6, 28
	s_add_i32 s7, s7, 28
	v_or_b32_e32 v178, s88, v1
	v_or_b32_e32 v180, s90, v1
	v_or_b32_e32 v183, s93, v0
	v_lshlrev_b64 v[138:139], 15, v[138:139]
	v_lshlrev_b64 v[140:141], 15, v[140:141]
	v_lshl_add_u64 v[134:135], v[22:23], 0, v[168:169]
	v_lshl_add_u64 v[136:137], v[22:23], 0, v[136:137]
	v_lshlrev_b64 v[150:151], 15, v[116:117]
	v_add_u32_e32 v116, s10, v181
	v_mov_b32_e32 v143, v7
	v_mov_b32_e32 v145, v7
	v_or_b32_e32 v182, s92, v1
	v_or_b32_e32 v184, s6, v1
	v_or_b32_e32 v185, s7, v0
	v_add_u32_e32 v142, s58, v178
; __device__ __forceinline__ void transpose_item(const float* __restrict__ W, int K, int N, int NV, bf16_t* __restrict__ WT, LAS float* scr, int item, int nblk, int lane, int mode, const float* __restrict__ kscale) {
;     ...
;     for (int i = 0; i < 32; ++i) { const int kk = 2 * i + (lane >> 5); float v = valid ? W[(size_t)(k0 + kk) * N + ns] : 0.f; if (kscale) v *= kscale[k0 + kk]; scr[kk * 33 + (lane & 31)] = v; }
	v_add_u32_e32 v144, s58, v180
	v_lshl_add_u64 v[138:139], v[22:23], 0, v[138:139]
	v_lshl_add_u64 v[140:141], v[22:23], 0, v[140:141]
	global_load_dword v190, v[134:135], off
	global_load_dword v191, v[138:139], off
	global_load_dword v192, v[136:137], off
	global_load_dword v193, v[140:141], off
	v_lshlrev_b64 v[136:137], 15, v[116:117]
	v_add_u32_e32 v116, s10, v183
	v_mov_b32_e32 v147, v7
	v_mov_b32_e32 v149, v7
	v_add_u32_e32 v146, s58, v182
	v_add_u32_e32 v148, s58, v184
	v_lshlrev_b64 v[142:143], 15, v[142:143]
	v_lshlrev_b64 v[144:145], 15, v[144:145]
	v_lshl_add_u64 v[134:135], v[22:23], 0, v[150:151]
	v_lshl_add_u64 v[136:137], v[22:23], 0, v[136:137]
	v_lshlrev_b64 v[138:139], 15, v[116:117]
	v_add_u32_e32 v116, s10, v185
	v_lshlrev_b64 v[146:147], 15, v[146:147]
	v_lshlrev_b64 v[148:149], 15, v[148:149]
	v_lshl_add_u64 v[142:143], v[22:23], 0, v[142:143]
	v_lshl_add_u64 v[144:145], v[22:23], 0, v[144:145]
	global_load_dword v194, v[134:135], off
	global_load_dword v195, v[142:143], off
	global_load_dword v196, v[136:137], off
	global_load_dword v197, v[144:145], off
	v_lshl_add_u64 v[134:135], v[22:23], 0, v[138:139]
	v_lshlrev_b64 v[136:137], 15, v[116:117]
	v_lshl_add_u64 v[146:147], v[22:23], 0, v[146:147]
	v_lshl_add_u64 v[148:149], v[22:23], 0, v[148:149]
	v_lshl_add_u64 v[136:137], v[22:23], 0, v[136:137]
	global_load_dword v116, v[134:135], off
	global_load_dword v198, v[146:147], off
	global_load_dword v199, v[136:137], off
	global_load_dword v200, v[148:149], off
	s_add_i32 s62, s62, 16
	s_add_i32 s59, s59, 16
	s_add_i32 s63, s63, -16
	v_mad_u64_u32 v[24:25], s[82:83], v61, s70, v[2:3]
	v_mad_u64_u32 v[26:27], s[82:83], v60, s70, v[2:3]
	v_mad_u64_u32 v[28:29], s[82:83], v63, s70, v[2:3]
	v_mad_u64_u32 v[30:31], s[82:83], v62, s70, v[2:3]
	v_mad_u64_u32 v[32:33], s[82:83], v65, s70, v[2:3]
	v_mad_u64_u32 v[34:35], s[82:83], v64, s70, v[2:3]
	v_mad_u64_u32 v[36:37], s[82:83], v67, s70, v[2:3]
	v_mad_u64_u32 v[38:39], s[82:83], v66, s70, v[2:3]
	v_mad_u64_u32 v[40:41], s[82:83], v69, s70, v[2:3]
	v_mad_u64_u32 v[56:57], s[82:83], v68, s70, v[2:3]
	v_mad_u64_u32 v[58:59], s[82:83], v71, s70, v[2:3]
	v_mad_u64_u32 v[60:61], s[82:83], v70, s70, v[2:3]
	v_mad_u64_u32 v[62:63], s[82:83], v73, s70, v[2:3]
	v_mad_u64_u32 v[64:65], s[82:83], v72, s70, v[2:3]
	v_mad_u64_u32 v[66:67], s[82:83], v75, s70, v[2:3]
	v_mad_u64_u32 v[68:69], s[82:83], v74, s70, v[2:3]
	s_waitcnt vmcnt(31)
	ds_write_b32 v24, v76
	s_waitcnt vmcnt(30)
	ds_write_b32 v26, v77
	s_waitcnt vmcnt(29)
	ds_write_b32 v28, v78
	s_waitcnt vmcnt(28)
	ds_write_b32 v30, v79
	s_waitcnt vmcnt(27)
	ds_write_b32 v32, v80
	s_waitcnt vmcnt(26)
	ds_write_b32 v34, v81
	s_waitcnt vmcnt(25)
	ds_write_b32 v36, v82
	s_waitcnt vmcnt(24)
	ds_write_b32 v38, v83
	s_waitcnt vmcnt(23)
	ds_write_b32 v40, v84
	s_waitcnt vmcnt(22)
	ds_write_b32 v56, v85
	s_waitcnt vmcnt(21)
	ds_write_b32 v58, v86
	s_waitcnt vmcnt(20)
	ds_write_b32 v60, v87
	s_waitcnt vmcnt(19)
	ds_write_b32 v62, v6
	s_waitcnt vmcnt(18)
	ds_write_b32 v64, v88
	s_waitcnt vmcnt(17)
	ds_write_b32 v66, v89
	s_waitcnt vmcnt(16)
	ds_write_b32 v68, v90
	v_mad_u64_u32 v[134:135], s[82:83], v171, s70, v[2:3]
	v_mad_u64_u32 v[136:137], s[82:83], v170, s70, v[2:3]
	v_mad_u64_u32 v[138:139], s[82:83], v173, s70, v[2:3]
	v_mad_u64_u32 v[140:141], s[82:83], v172, s70, v[2:3]
	v_mad_u64_u32 v[142:143], s[82:83], v175, s70, v[2:3]
	v_mad_u64_u32 v[144:145], s[82:83], v174, s70, v[2:3]
	v_mad_u64_u32 v[146:147], s[82:83], v177, s70, v[2:3]
	v_mad_u64_u32 v[148:149], s[82:83], v176, s70, v[2:3]
	v_mad_u64_u32 v[150:151], s[82:83], v179, s70, v[2:3]
	v_mad_u64_u32 v[166:167], s[82:83], v178, s70, v[2:3]
	v_mad_u64_u32 v[168:169], s[82:83], v181, s70, v[2:3]
	v_mad_u64_u32 v[170:171], s[82:83], v180, s70, v[2:3]
	v_mad_u64_u32 v[172:173], s[82:83], v183, s70, v[2:3]
	v_mad_u64_u32 v[174:175], s[82:83], v182, s70, v[2:3]
	v_mad_u64_u32 v[176:177], s[82:83], v185, s70, v[2:3]
	v_mad_u64_u32 v[178:179], s[82:83], v184, s70, v[2:3]
	s_waitcnt vmcnt(15)
; #define LAS __attribute__((address_space(3)))
; __device__ __forceinline__ unsigned pk_bf16(float lo, float hi) { f32x2 v = {lo, hi}; bf16x2_t b = __builtin_convertvector(v, bf16x2_t); return __builtin_bit_cast(unsigned, b); }
; __device__ __forceinline__ void transpose_item(const float* __restrict__ W, int K, int N, int NV, bf16_t* __restrict__ WT, LAS float* scr, int item, int nblk, int lane, int mode, const float* __restrict__ kscale) {
;     ...
;     for (int i = 0; i < 32; ++i) { const int kk = 2 * i + (lane >> 5); float v = valid ? W[(size_t)(k0 + kk) * N + ns] : 0.f; if (kscale) v *= kscale[k0 + kk]; scr[kk * 33 + (lane & 31)] = v; }
;     asm volatile("s_waitcnt lgkmcnt(0)" ::: "memory");
;     const int c = lane & 7;
; #pragma unroll
;     for (int j = 0; j < 4; ++j) { const int n = (lane >> 3) + 8 * j; const LAS float* s = scr + (8 * c) * 33 + n;
;         u32x4 o; o.x = pk_bf16(s[0 * 33], s[1 * 33]); o.y = pk_bf16(s[2 * 33], s[3 * 33]); o.z = pk_bf16(s[4 * 33], s[5 * 33]); o.w = pk_bf16(s[6 * 33], s[7 * 33]);
;         *(u32x4*)(WT + (size_t)(n0 + n) * K + k0 + 8 * c) = o; }
;     asm volatile("s_waitcnt lgkmcnt(0)" ::: "memory");
	ds_write_b32 v134, v186
	s_waitcnt vmcnt(14)
	ds_write_b32 v136, v187
	s_waitcnt vmcnt(13)
	ds_write_b32 v138, v188
	s_waitcnt vmcnt(12)
	ds_write_b32 v140, v189
	s_waitcnt vmcnt(11)
	ds_write_b32 v142, v190
	s_waitcnt vmcnt(10)
	ds_write_b32 v144, v191
	s_waitcnt vmcnt(9)
	ds_write_b32 v146, v192
	s_waitcnt vmcnt(8)
	ds_write_b32 v148, v193
	s_waitcnt vmcnt(7)
	ds_write_b32 v150, v194
	s_waitcnt vmcnt(6)
	ds_write_b32 v166, v195
	s_waitcnt vmcnt(5)
	ds_write_b32 v168, v196
	s_waitcnt vmcnt(4)
	ds_write_b32 v170, v197
	s_waitcnt vmcnt(3)
	ds_write_b32 v172, v116
	s_waitcnt vmcnt(2)
	ds_write_b32 v174, v198
	s_waitcnt vmcnt(1)
	ds_write_b32 v176, v199
	s_waitcnt vmcnt(0)
	ds_write_b32 v178, v200
	s_lshl_b64 s[0:1], s[0:1], 1
	s_add_u32 s0, s68, s0
	s_waitcnt lgkmcnt(0)
	s_addc_u32 s1, s69, s1
	s_lshl_b32 s6, s10, 1
	ds_read2_b32 v[26:27], v42 offset0:33 offset1:41
	ds_read2_b32 v[28:29], v42 offset1:8
	ds_read2_b32 v[30:31], v42 offset0:66 offset1:74
	ds_read2_b32 v[32:33], v42 offset0:99 offset1:107
	ds_read2_b32 v[34:35], v42 offset0:132 offset1:140
	ds_read2_b32 v[36:37], v42 offset0:165 offset1:173
	ds_read2_b32 v[38:39], v42 offset0:198 offset1:206
	ds_read2_b32 v[40:41], v42 offset0:231 offset1:239
	s_add_u32 s0, s0, s6
	s_addc_u32 s1, s1, 0
	v_lshlrev_b32_e32 v6, 1, v4
	v_lshl_add_u64 v[56:57], s[0:1], 0, v[6:7]
	v_or_b32_e32 v6, s9, v21
	v_lshlrev_b32_e32 v6, 12, v6
	s_waitcnt lgkmcnt(6)
	v_cvt_pk_bf16_f32 v22, v28, v26
	s_waitcnt lgkmcnt(4)
	v_cvt_pk_bf16_f32 v23, v30, v32
	s_waitcnt lgkmcnt(2)
	v_cvt_pk_bf16_f32 v24, v34, v36
	s_waitcnt lgkmcnt(0)
	v_cvt_pk_bf16_f32 v25, v38, v40
	v_lshl_add_u64 v[58:59], v[56:57], 0, v[6:7]
	global_store_dwordx4 v[58:59], v[22:25], off
	v_or_b32_e32 v6, s9, v43
	v_lshlrev_b32_e32 v6, 12, v6
	v_cvt_pk_bf16_f32 v22, v29, v27
	v_cvt_pk_bf16_f32 v23, v31, v33
	v_cvt_pk_bf16_f32 v24, v35, v37
	v_cvt_pk_bf16_f32 v25, v39, v41
	ds_read2_b32 v[28:29], v42 offset0:49 offset1:57
	ds_read2_b32 v[30:31], v42 offset0:16 offset1:24
	ds_read2_b32 v[32:33], v42 offset0:82 offset1:90
	ds_read2_b32 v[34:35], v42 offset0:115 offset1:123
	ds_read2_b32 v[36:37], v42 offset0:148 offset1:156
	ds_read2_b32 v[38:39], v42 offset0:181 offset1:189
	ds_read2_b32 v[40:41], v42 offset0:214 offset1:222
	ds_read2_b32 v[58:59], v42 offset0:247 offset1:255
	v_lshl_add_u64 v[26:27], v[56:57], 0, v[6:7]
	v_or_b32_e32 v6, s9, v44
	v_lshlrev_b32_e32 v6, 12, v6
	global_store_dwordx4 v[26:27], v[22:25], off
	v_lshl_add_u64 v[26:27], v[56:57], 0, v[6:7]
	v_or_b32_e32 v6, s9, v45
	s_waitcnt lgkmcnt(6)
	v_cvt_pk_bf16_f32 v22, v30, v28
	s_waitcnt lgkmcnt(4)
	v_cvt_pk_bf16_f32 v23, v32, v34
	s_waitcnt lgkmcnt(2)
	v_cvt_pk_bf16_f32 v24, v36, v38
	s_waitcnt lgkmcnt(0)
	v_cvt_pk_bf16_f32 v25, v40, v58
	v_lshlrev_b32_e32 v6, 12, v6
	global_store_dwordx4 v[26:27], v[22:25], off
	v_lshl_add_u64 v[26:27], v[56:57], 0, v[6:7]
	v_readlane_b32 s92, v242, 2
	v_cvt_pk_bf16_f32 v22, v31, v29
	v_cvt_pk_bf16_f32 v23, v33, v35
	v_cvt_pk_bf16_f32 v24, v37, v39
	v_cvt_pk_bf16_f32 v25, v41, v59
	global_store_dwordx4 v[26:27], v[22:25], off
	s_waitcnt lgkmcnt(0)
	v_readlane_b32 s88, v242, 4
	v_readlane_b32 s84, v242, 1
	v_readlane_b32 s93, v242, 3
	v_readlane_b32 s89, v242, 5

; __device__ __forceinline__ void transpose_item(const float* __restrict__ W, int K, int N, int NV, bf16_t* __restrict__ WT, LAS float* scr, int item, int nblk, int lane, int mode, const float* __restrict__ kscale) {
;     const int kb = item / nblk, nb = item % nblk, k0 = 64 * kb, n0 = 32 * nb;
;     const int nd = n0 + (lane & 31); const bool valid = nd < NV; const int ns = valid ? srccol(mode, nd) : 0;
; #pragma unroll 8
;     for (int i = 0; i < 32; ++i) { const int kk = 2 * i + (lane >> 5); float v = valid ? W[(size_t)(k0 + kk) * N + ns] : 0.f; if (kscale) v *= kscale[k0 + kk]; scr[kk * 33 + (lane & 31)] = v; }
.LBB0_65:
	s_lshl_b32 s6, s10, 1
	s_lshl_b32 s7, s58, 1
	v_or_b32_e32 v61, s7, v0
	s_add_i32 s34, s6, 4
	s_add_i32 s35, s7, 4
	s_add_i32 s63, s7, 8
	v_add_u32_e32 v6, s1, v61
	v_or_b32_e32 v62, s34, v1
	v_or_b32_e32 v63, s35, v0
	v_mov_b32_e32 v27, v7
	v_or_b32_e32 v60, s6, v1
	s_add_i32 s83, s7, 12
	v_or_b32_e32 v65, s63, v0
	v_lshlrev_b64 v[40:41], 13, v[6:7]
	v_add_u32_e32 v26, s9, v62
	v_add_u32_e32 v6, s1, v63
	v_mov_b32_e32 v25, v7
	s_add_i32 s62, s6, 8
	s_add_i32 s82, s6, 12
	s_add_i32 s87, s7, 16
	v_add_u32_e32 v24, s9, v60
	v_or_b32_e32 v67, s83, v0
	v_lshlrev_b64 v[26:27], 13, v[26:27]
	v_lshlrev_b64 v[56:57], 13, v[6:7]
	v_add_u32_e32 v6, s1, v65
	s_add_i32 s89, s7, 20
	v_or_b32_e32 v64, s62, v1
	v_or_b32_e32 v66, s82, v1
	v_or_b32_e32 v69, s87, v0
	v_lshlrev_b64 v[24:25], 13, v[24:25]
	v_lshl_add_u64 v[40:41], v[22:23], 0, v[40:41]
	v_lshl_add_u64 v[26:27], v[22:23], 0, v[26:27]
	v_lshlrev_b64 v[58:59], 13, v[6:7]
	v_add_u32_e32 v6, s1, v67
	v_mov_b32_e32 v29, v7
	v_mov_b32_e32 v31, v7
	s_add_i32 s86, s6, 16
	s_add_i32 s88, s6, 20
	s_add_i32 s91, s7, 24
	v_or_b32_e32 v71, s89, v0
	v_add_u32_e32 v28, s9, v64
	v_add_u32_e32 v30, s9, v66
	v_lshl_add_u64 v[24:25], v[22:23], 0, v[24:25]
	v_lshl_add_u64 v[56:57], v[22:23], 0, v[56:57]
	global_load_dword v76, v[40:41], off
	global_load_dword v77, v[24:25], off
	global_load_dword v78, v[56:57], off
	global_load_dword v79, v[26:27], off
	v_lshlrev_b64 v[26:27], 13, v[6:7]
	v_add_u32_e32 v6, s1, v69
	s_add_i32 s90, s6, 24
	s_add_i32 s6, s6, 28
	s_add_i32 s7, s7, 28
	v_or_b32_e32 v68, s86, v1
	v_or_b32_e32 v70, s88, v1
	v_or_b32_e32 v73, s91, v0
	v_lshlrev_b64 v[28:29], 13, v[28:29]
	v_lshlrev_b64 v[30:31], 13, v[30:31]
	v_lshl_add_u64 v[24:25], v[22:23], 0, v[58:59]
	v_lshl_add_u64 v[26:27], v[22:23], 0, v[26:27]
	v_lshlrev_b64 v[40:41], 13, v[6:7]
	v_add_u32_e32 v6, s1, v71
	v_mov_b32_e32 v33, v7
	v_mov_b32_e32 v35, v7
	v_or_b32_e32 v72, s90, v1
	v_or_b32_e32 v74, s6, v1
	v_or_b32_e32 v75, s7, v0
	v_add_u32_e32 v32, s9, v68
	v_add_u32_e32 v34, s9, v70
	v_lshl_add_u64 v[28:29], v[22:23], 0, v[28:29]
	v_lshl_add_u64 v[30:31], v[22:23], 0, v[30:31]
	global_load_dword v80, v[24:25], off
	global_load_dword v81, v[28:29], off
	global_load_dword v82, v[26:27], off
	global_load_dword v83, v[30:31], off
	v_lshlrev_b64 v[26:27], 13, v[6:7]
	v_add_u32_e32 v6, s1, v73
	v_mov_b32_e32 v37, v7
	v_mov_b32_e32 v39, v7
	v_add_u32_e32 v36, s9, v72
	v_add_u32_e32 v38, s9, v74
	v_lshlrev_b64 v[32:33], 13, v[32:33]
	v_lshlrev_b64 v[34:35], 13, v[34:35]
	v_lshl_add_u64 v[24:25], v[22:23], 0, v[40:41]
	v_lshl_add_u64 v[26:27], v[22:23], 0, v[26:27]
	v_lshlrev_b64 v[28:29], 13, v[6:7]
	v_add_u32_e32 v6, s1, v75
	v_lshlrev_b64 v[36:37], 13, v[36:37]
	v_lshlrev_b64 v[38:39], 13, v[38:39]
	v_lshl_add_u64 v[32:33], v[22:23], 0, v[32:33]
	v_lshl_add_u64 v[34:35], v[22:23], 0, v[34:35]
	global_load_dword v84, v[24:25], off
	global_load_dword v85, v[32:33], off
	global_load_dword v86, v[26:27], off
	global_load_dword v87, v[34:35], off
	v_lshl_add_u64 v[24:25], v[22:23], 0, v[28:29]
	v_lshlrev_b64 v[26:27], 13, v[6:7]
	v_lshl_add_u64 v[36:37], v[22:23], 0, v[36:37]
	v_lshl_add_u64 v[38:39], v[22:23], 0, v[38:39]
	v_lshl_add_u64 v[26:27], v[22:23], 0, v[26:27]
	global_load_dword v6, v[24:25], off
	global_load_dword v88, v[36:37], off
	global_load_dword v89, v[26:27], off
	global_load_dword v90, v[38:39], off
	s_add_i32 s58, s58, 16
	s_add_i32 s10, s10, 16
	s_add_i32 s59, s59, -16
	v_mov_b32_e32 v117, v7
	s_lshl_b32 s6, s10, 1
	s_lshl_b32 s7, s58, 1
	v_or_b32_e32 v171, s7, v0
	s_add_i32 s34, s6, 4
	s_add_i32 s35, s7, 4
	s_add_i32 s63, s7, 8
	v_add_u32_e32 v116, s1, v171
	v_or_b32_e32 v172, s34, v1
	v_or_b32_e32 v173, s35, v0
	v_mov_b32_e32 v137, v7
	v_or_b32_e32 v170, s6, v1
	s_add_i32 s83, s7, 12
	v_or_b32_e32 v175, s63, v0
	v_lshlrev_b64 v[150:151], 13, v[116:117]
	v_add_u32_e32 v136, s9, v172
	v_add_u32_e32 v116, s1, v173
	v_mov_b32_e32 v135, v7
	s_add_i32 s62, s6, 8
	s_add_i32 s82, s6, 12
	s_add_i32 s87, s7, 16
	v_add_u32_e32 v134, s9, v170
	v_or_b32_e32 v177, s83, v0
	v_lshlrev_b64 v[136:137], 13, v[136:137]
	v_lshlrev_b64 v[166:167], 13, v[116:117]
	v_add_u32_e32 v116, s1, v175
	s_add_i32 s89, s7, 20
	v_or_b32_e32 v174, s62, v1
	v_or_b32_e32 v176, s82, v1
	v_or_b32_e32 v179, s87, v0
	v_lshlrev_b64 v[134:135], 13, v[134:135]
	v_lshl_add_u64 v[150:151], v[22:23], 0, v[150:151]
	v_lshl_add_u64 v[136:137], v[22:23], 0, v[136:137]
	v_lshlrev_b64 v[168:169], 13, v[116:117]
	v_add_u32_e32 v116, s1, v177
	v_mov_b32_e32 v139, v7
	v_mov_b32_e32 v141, v7
	s_add_i32 s86, s6, 16
	s_add_i32 s88, s6, 20
	s_add_i32 s91, s7, 24
	v_or_b32_e32 v181, s89, v0
	v_add_u32_e32 v138, s9, v174
	v_add_u32_e32 v140, s9, v176
	v_lshl_add_u64 v[134:135], v[22:23], 0, v[134:135]
	v_lshl_add_u64 v[166:167], v[22:23], 0, v[166:167]
	global_load_dword v186, v[150:151], off
	global_load_dword v187, v[134:135], off
	global_load_dword v188, v[166:167], off
	global_load_dword v189, v[136:137], off
	v_lshlrev_b64 v[136:137], 13, v[116:117]
	v_add_u32_e32 v116, s1, v179
	s_add_i32 s90, s6, 24
	s_add_i32 s6, s6, 28
	s_add_i32 s7, s7, 28
	v_or_b32_e32 v178, s86, v1
	v_or_b32_e32 v180, s88, v1
	v_or_b32_e32 v183, s91, v0
	v_lshlrev_b64 v[138:139], 13, v[138:139]
	v_lshlrev_b64 v[140:141], 13, v[140:141]
	v_lshl_add_u64 v[134:135], v[22:23], 0, v[168:169]
	v_lshl_add_u64 v[136:137], v[22:23], 0, v[136:137]
	v_lshlrev_b64 v[150:151], 13, v[116:117]
	v_add_u32_e32 v116, s1, v181
	v_mov_b32_e32 v143, v7
	v_mov_b32_e32 v145, v7
	v_or_b32_e32 v182, s90, v1
	v_or_b32_e32 v184, s6, v1
	v_or_b32_e32 v185, s7, v0
	v_add_u32_e32 v142, s9, v178
	v_add_u32_e32 v144, s9, v180
; #define LAS __attribute__((address_space(3)))
; __device__ __forceinline__ unsigned pk_bf16(float lo, float hi) { f32x2 v = {lo, hi}; bf16x2_t b = __builtin_convertvector(v, bf16x2_t); return __builtin_bit_cast(unsigned, b); }
; __device__ __forceinline__ void transpose_item(const float* __restrict__ W, int K, int N, int NV, bf16_t* __restrict__ WT, LAS float* scr, int item, int nblk, int lane, int mode, const float* __restrict__ kscale) {
;     ...
;     for (int i = 0; i < 32; ++i) { const int kk = 2 * i + (lane >> 5); float v = valid ? W[(size_t)(k0 + kk) * N + ns] : 0.f; if (kscale) v *= kscale[k0 + kk]; scr[kk * 33 + (lane & 31)] = v; }
;     asm volatile("s_waitcnt lgkmcnt(0)" ::: "memory");
;     const int c = lane & 7;
; #pragma unroll
;     for (int j = 0; j < 4; ++j) { const int n = (lane >> 3) + 8 * j; const LAS float* s = scr + (8 * c) * 33 + n;
;         u32x4 o; o.x = pk_bf16(s[0 * 33], s[1 * 33]); o.y = pk_bf16(s[2 * 33], s[3 * 33]); o.z = pk_bf16(s[4 * 33], s[5 * 33]); o.w = pk_bf16(s[6 * 33], s[7 * 33]);
;         *(u32x4*)(WT + (size_t)(n0 + n) * K + k0 + 8 * c) = o; }
;     asm volatile("s_waitcnt lgkmcnt(0)" ::: "memory");
	v_lshl_add_u64 v[138:139], v[22:23], 0, v[138:139]
	v_lshl_add_u64 v[140:141], v[22:23], 0, v[140:141]
	global_load_dword v190, v[134:135], off
	global_load_dword v191, v[138:139], off
	global_load_dword v192, v[136:137], off
	global_load_dword v193, v[140:141], off
	v_lshlrev_b64 v[136:137], 13, v[116:117]
	v_add_u32_e32 v116, s1, v183
	v_mov_b32_e32 v147, v7
	v_mov_b32_e32 v149, v7
	v_add_u32_e32 v146, s9, v182
	v_add_u32_e32 v148, s9, v184
	v_lshlrev_b64 v[142:143], 13, v[142:143]
	v_lshlrev_b64 v[144:145], 13, v[144:145]
	v_lshl_add_u64 v[134:135], v[22:23], 0, v[150:151]
	v_lshl_add_u64 v[136:137], v[22:23], 0, v[136:137]
	v_lshlrev_b64 v[138:139], 13, v[116:117]
	v_add_u32_e32 v116, s1, v185
	v_lshlrev_b64 v[146:147], 13, v[146:147]
	v_lshlrev_b64 v[148:149], 13, v[148:149]
	v_lshl_add_u64 v[142:143], v[22:23], 0, v[142:143]
	v_lshl_add_u64 v[144:145], v[22:23], 0, v[144:145]
	global_load_dword v194, v[134:135], off
	global_load_dword v195, v[142:143], off
	global_load_dword v196, v[136:137], off
	global_load_dword v197, v[144:145], off
	v_lshl_add_u64 v[134:135], v[22:23], 0, v[138:139]
	v_lshlrev_b64 v[136:137], 13, v[116:117]
	v_lshl_add_u64 v[146:147], v[22:23], 0, v[146:147]
	v_lshl_add_u64 v[148:149], v[22:23], 0, v[148:149]
	v_lshl_add_u64 v[136:137], v[22:23], 0, v[136:137]
	global_load_dword v116, v[134:135], off
	global_load_dword v198, v[146:147], off
	global_load_dword v199, v[136:137], off
	global_load_dword v200, v[148:149], off
	s_add_i32 s58, s58, 16
	s_add_i32 s10, s10, 16
	s_add_i32 s59, s59, -16
	v_mad_u64_u32 v[24:25], s[62:63], v61, s70, v[2:3]
	v_mad_u64_u32 v[26:27], s[62:63], v60, s70, v[2:3]
	v_mad_u64_u32 v[28:29], s[62:63], v63, s70, v[2:3]
	v_mad_u64_u32 v[30:31], s[62:63], v62, s70, v[2:3]
	v_mad_u64_u32 v[32:33], s[62:63], v65, s70, v[2:3]
	v_mad_u64_u32 v[34:35], s[62:63], v64, s70, v[2:3]
	v_mad_u64_u32 v[36:37], s[62:63], v67, s70, v[2:3]
	v_mad_u64_u32 v[38:39], s[62:63], v66, s70, v[2:3]
	v_mad_u64_u32 v[40:41], s[62:63], v69, s70, v[2:3]
	v_mad_u64_u32 v[56:57], s[62:63], v68, s70, v[2:3]
	v_mad_u64_u32 v[58:59], s[62:63], v71, s70, v[2:3]
	v_mad_u64_u32 v[60:61], s[62:63], v70, s70, v[2:3]
	v_mad_u64_u32 v[62:63], s[62:63], v73, s70, v[2:3]
	v_mad_u64_u32 v[64:65], s[62:63], v72, s70, v[2:3]
	v_mad_u64_u32 v[66:67], s[62:63], v75, s70, v[2:3]
	v_mad_u64_u32 v[68:69], s[62:63], v74, s70, v[2:3]
	s_waitcnt vmcnt(31)
	ds_write_b32 v24, v76
	s_waitcnt vmcnt(30)
	ds_write_b32 v26, v77
	s_waitcnt vmcnt(29)
	ds_write_b32 v28, v78
	s_waitcnt vmcnt(28)
	ds_write_b32 v30, v79
	s_waitcnt vmcnt(27)
	ds_write_b32 v32, v80
	s_waitcnt vmcnt(26)
	ds_write_b32 v34, v81
	s_waitcnt vmcnt(25)
	ds_write_b32 v36, v82
	s_waitcnt vmcnt(24)
	ds_write_b32 v38, v83
	s_waitcnt vmcnt(23)
	ds_write_b32 v40, v84
	s_waitcnt vmcnt(22)
	ds_write_b32 v56, v85
	s_waitcnt vmcnt(21)
	ds_write_b32 v58, v86
	s_waitcnt vmcnt(20)
	ds_write_b32 v60, v87
	s_waitcnt vmcnt(19)
	ds_write_b32 v62, v6
	s_waitcnt vmcnt(18)
	ds_write_b32 v64, v88
	s_waitcnt vmcnt(17)
	ds_write_b32 v66, v89
	s_waitcnt vmcnt(16)
	ds_write_b32 v68, v90
	v_mad_u64_u32 v[134:135], s[62:63], v171, s70, v[2:3]
	v_mad_u64_u32 v[136:137], s[62:63], v170, s70, v[2:3]
	v_mad_u64_u32 v[138:139], s[62:63], v173, s70, v[2:3]
	v_mad_u64_u32 v[140:141], s[62:63], v172, s70, v[2:3]
	v_mad_u64_u32 v[142:143], s[62:63], v175, s70, v[2:3]
	v_mad_u64_u32 v[144:145], s[62:63], v174, s70, v[2:3]
	v_mad_u64_u32 v[146:147], s[62:63], v177, s70, v[2:3]
	v_mad_u64_u32 v[148:149], s[62:63], v176, s70, v[2:3]
	v_mad_u64_u32 v[150:151], s[62:63], v179, s70, v[2:3]
	v_mad_u64_u32 v[166:167], s[62:63], v178, s70, v[2:3]
	v_mad_u64_u32 v[168:169], s[62:63], v181, s70, v[2:3]
	v_mad_u64_u32 v[170:171], s[62:63], v180, s70, v[2:3]
	v_mad_u64_u32 v[172:173], s[62:63], v183, s70, v[2:3]
	v_mad_u64_u32 v[174:175], s[62:63], v182, s70, v[2:3]
	v_mad_u64_u32 v[176:177], s[62:63], v185, s70, v[2:3]
	v_mad_u64_u32 v[178:179], s[62:63], v184, s70, v[2:3]
	s_waitcnt vmcnt(15)
	ds_write_b32 v134, v186
	s_waitcnt vmcnt(14)
	ds_write_b32 v136, v187
	s_waitcnt vmcnt(13)
	ds_write_b32 v138, v188
	s_waitcnt vmcnt(12)
	ds_write_b32 v140, v189
	s_waitcnt vmcnt(11)
	ds_write_b32 v142, v190
	s_waitcnt vmcnt(10)
	ds_write_b32 v144, v191
	s_waitcnt vmcnt(9)
	ds_write_b32 v146, v192
	s_waitcnt vmcnt(8)
	ds_write_b32 v148, v193
	s_waitcnt vmcnt(7)
	ds_write_b32 v150, v194
	s_waitcnt vmcnt(6)
	ds_write_b32 v166, v195
	s_waitcnt vmcnt(5)
	ds_write_b32 v168, v196
	s_waitcnt vmcnt(4)
	ds_write_b32 v170, v197
	s_waitcnt vmcnt(3)
	ds_write_b32 v172, v116
	s_waitcnt vmcnt(2)
	ds_write_b32 v174, v198
	s_waitcnt vmcnt(1)
	ds_write_b32 v176, v199
	s_waitcnt vmcnt(0)
	ds_write_b32 v178, v200
	s_waitcnt lgkmcnt(0)
	ds_read2_b32 v[26:27], v42 offset0:33 offset1:41
	ds_read2_b32 v[28:29], v42 offset1:8
	ds_read2_b32 v[30:31], v42 offset0:66 offset1:74
	ds_read2_b32 v[32:33], v42 offset0:99 offset1:107
	ds_read2_b32 v[34:35], v42 offset0:132 offset1:140
	ds_read2_b32 v[36:37], v42 offset0:165 offset1:173
	ds_read2_b32 v[38:39], v42 offset0:198 offset1:206
	ds_read2_b32 v[40:41], v42 offset0:231 offset1:239
	s_lshl_b32 s10, s1, 1
	v_or_b32_e32 v6, s0, v21
	v_lshl_add_u64 v[56:57], v[8:9], 0, s[10:11]
	v_lshlrev_b32_e32 v6, 12, v6
	s_waitcnt lgkmcnt(6)
	v_cvt_pk_bf16_f32 v22, v28, v26
	s_waitcnt lgkmcnt(4)
	v_cvt_pk_bf16_f32 v23, v30, v32
	s_waitcnt lgkmcnt(2)
	v_cvt_pk_bf16_f32 v24, v34, v36
	s_waitcnt lgkmcnt(0)
	v_cvt_pk_bf16_f32 v25, v38, v40
	v_lshl_add_u64 v[58:59], v[56:57], 0, v[6:7]
	global_store_dwordx4 v[58:59], v[22:25], off
	v_or_b32_e32 v6, s0, v43
	v_lshlrev_b32_e32 v6, 12, v6
	v_cvt_pk_bf16_f32 v22, v29, v27
	v_cvt_pk_bf16_f32 v23, v31, v33
	v_cvt_pk_bf16_f32 v24, v35, v37
	v_cvt_pk_bf16_f32 v25, v39, v41
	ds_read2_b32 v[28:29], v42 offset0:49 offset1:57
	ds_read2_b32 v[30:31], v42 offset0:16 offset1:24
	ds_read2_b32 v[32:33], v42 offset0:82 offset1:90
	ds_read2_b32 v[34:35], v42 offset0:115 offset1:123
	ds_read2_b32 v[36:37], v42 offset0:148 offset1:156
	ds_read2_b32 v[38:39], v42 offset0:181 offset1:189
	ds_read2_b32 v[40:41], v42 offset0:214 offset1:222
	ds_read2_b32 v[58:59], v42 offset0:247 offset1:255
	v_lshl_add_u64 v[26:27], v[56:57], 0, v[6:7]
	v_or_b32_e32 v6, s0, v44
	v_lshlrev_b32_e32 v6, 12, v6
	global_store_dwordx4 v[26:27], v[22:25], off
	v_lshl_add_u64 v[26:27], v[56:57], 0, v[6:7]
	v_or_b32_e32 v6, s0, v45
	s_waitcnt lgkmcnt(6)
	v_cvt_pk_bf16_f32 v22, v30, v28
	s_waitcnt lgkmcnt(4)
	v_cvt_pk_bf16_f32 v23, v32, v34
	s_waitcnt lgkmcnt(2)
	v_cvt_pk_bf16_f32 v24, v36, v38
	s_waitcnt lgkmcnt(0)
	v_cvt_pk_bf16_f32 v25, v40, v58
	v_lshlrev_b32_e32 v6, 12, v6
	global_store_dwordx4 v[26:27], v[22:25], off
	v_lshl_add_u64 v[26:27], v[56:57], 0, v[6:7]
	v_readlane_b32 s88, v242, 4
	v_cvt_pk_bf16_f32 v22, v31, v29
	v_cvt_pk_bf16_f32 v23, v33, v35
	v_cvt_pk_bf16_f32 v24, v37, v39
	v_cvt_pk_bf16_f32 v25, v41, v59
	global_store_dwordx4 v[26:27], v[22:25], off
	s_waitcnt lgkmcnt(0)
	v_readlane_b32 s89, v242, 5

; __device__ __forceinline__ void transpose_item(const float* __restrict__ W, int K, int N, int NV, bf16_t* __restrict__ WT, LAS float* scr, int item, int nblk, int lane, int mode, const float* __restrict__ kscale) {
;     const int kb = item / nblk, nb = item % nblk, k0 = 64 * kb, n0 = 32 * nb;
;     const int nd = n0 + (lane & 31); const bool valid = nd < NV; const int ns = valid ? srccol(mode, nd) : 0;
; #pragma unroll 8
;     for (int i = 0; i < 32; ++i) { const int kk = 2 * i + (lane >> 5); float v = valid ? W[(size_t)(k0 + kk) * N + ns] : 0.f; if (kscale) v *= kscale[k0 + kk]; scr[kk * 33 + (lane & 31)] = v; }
.LBB0_72:
	s_lshl_b32 s6, s10, 1
	s_lshl_b32 s7, s58, 1
	v_or_b32_e32 v6, s6, v1
	v_or_b32_e32 v70, s7, v0
	s_add_i32 s34, s6, 4
	s_add_i32 s35, s7, 4
	s_add_i32 s62, s6, 8
	s_add_i32 s63, s7, 8
	s_add_i32 s82, s6, 12
	s_add_i32 s83, s7, 12
	s_add_i32 s86, s6, 16
	s_add_i32 s87, s7, 16
	s_add_i32 s88, s6, 20
	s_add_i32 s89, s7, 20
	s_add_i32 s90, s6, 24
	s_add_i32 s91, s7, 24
	s_add_i32 s6, s6, 28
	s_add_i32 s7, s7, 28
	v_add_u32_e32 v24, s1, v70
	v_or_b32_e32 v71, s34, v1
	v_or_b32_e32 v72, s35, v0
	v_or_b32_e32 v73, s62, v1
	v_or_b32_e32 v74, s63, v0
	v_or_b32_e32 v75, s82, v1
	v_or_b32_e32 v76, s83, v0
	v_or_b32_e32 v77, s86, v1
	v_or_b32_e32 v78, s87, v0
	v_or_b32_e32 v79, s88, v1
	v_or_b32_e32 v80, s89, v0
	v_or_b32_e32 v81, s90, v1
	v_or_b32_e32 v82, s91, v0
	v_or_b32_e32 v83, s6, v1
	v_or_b32_e32 v84, s7, v0
	v_add_u32_e32 v26, s9, v6
	v_mad_u64_u32 v[24:25], s[62:63], v24, s76, v[22:23]
	v_add_u32_e32 v30, s9, v71
	v_add_u32_e32 v28, s1, v72
	v_add_u32_e32 v34, s9, v73
	v_add_u32_e32 v32, s1, v74
	v_add_u32_e32 v38, s9, v75
	v_add_u32_e32 v36, s1, v76
	v_add_u32_e32 v56, s9, v77
	v_add_u32_e32 v40, s1, v78
	v_add_u32_e32 v60, s9, v79
	v_add_u32_e32 v58, s1, v80
	v_add_u32_e32 v64, s9, v81
	v_add_u32_e32 v62, s1, v82
	v_add_u32_e32 v68, s9, v83
	v_add_u32_e32 v66, s1, v84
	v_mad_u64_u32 v[26:27], s[62:63], v26, s76, v[22:23]
	v_mad_u64_u32 v[28:29], s[62:63], v28, s76, v[22:23]
	v_mad_u64_u32 v[30:31], s[62:63], v30, s76, v[22:23]
	v_mad_u64_u32 v[32:33], s[62:63], v32, s76, v[22:23]
	v_mad_u64_u32 v[34:35], s[62:63], v34, s76, v[22:23]
	v_mad_u64_u32 v[36:37], s[62:63], v36, s76, v[22:23]
	v_mad_u64_u32 v[38:39], s[62:63], v38, s76, v[22:23]
	v_mad_u64_u32 v[40:41], s[62:63], v40, s76, v[22:23]
	v_mad_u64_u32 v[56:57], s[62:63], v56, s76, v[22:23]
	v_mad_u64_u32 v[58:59], s[62:63], v58, s76, v[22:23]
	v_mad_u64_u32 v[60:61], s[62:63], v60, s76, v[22:23]
	v_mad_u64_u32 v[62:63], s[62:63], v62, s76, v[22:23]
	v_mad_u64_u32 v[64:65], s[62:63], v64, s76, v[22:23]
	v_mad_u64_u32 v[66:67], s[62:63], v66, s76, v[22:23]
	v_mad_u64_u32 v[68:69], s[62:63], v68, s76, v[22:23]
	global_load_dword v85, v[24:25], off
	global_load_dword v86, v[26:27], off
	global_load_dword v87, v[28:29], off
	global_load_dword v88, v[30:31], off
	global_load_dword v89, v[32:33], off
	global_load_dword v90, v[34:35], off
	global_load_dword v91, v[36:37], off
	global_load_dword v92, v[38:39], off
	global_load_dword v93, v[40:41], off
	global_load_dword v94, v[56:57], off
	global_load_dword v95, v[58:59], off
	global_load_dword v96, v[60:61], off
	global_load_dword v97, v[62:63], off
	global_load_dword v98, v[64:65], off
	global_load_dword v99, v[66:67], off
	global_load_dword v100, v[68:69], off
	s_add_i32 s58, s58, 16
	s_add_i32 s10, s10, 16
	s_add_i32 s59, s59, -16
	s_lshl_b32 s6, s10, 1
	s_lshl_b32 s7, s58, 1
	v_or_b32_e32 v116, s6, v1
	v_or_b32_e32 v180, s7, v0
	s_add_i32 s34, s6, 4
	s_add_i32 s35, s7, 4
	s_add_i32 s62, s6, 8
	s_add_i32 s63, s7, 8
	s_add_i32 s82, s6, 12
	s_add_i32 s83, s7, 12
	s_add_i32 s86, s6, 16
	s_add_i32 s87, s7, 16
	s_add_i32 s88, s6, 20
	s_add_i32 s89, s7, 20
	s_add_i32 s90, s6, 24
	s_add_i32 s91, s7, 24
	s_add_i32 s6, s6, 28
	s_add_i32 s7, s7, 28
	v_add_u32_e32 v134, s1, v180
	v_or_b32_e32 v181, s34, v1
	v_or_b32_e32 v182, s35, v0
	v_or_b32_e32 v183, s62, v1
	v_or_b32_e32 v184, s63, v0
	v_or_b32_e32 v185, s82, v1
	v_or_b32_e32 v186, s83, v0
	v_or_b32_e32 v187, s86, v1
	v_or_b32_e32 v188, s87, v0
	v_or_b32_e32 v189, s88, v1
	v_or_b32_e32 v190, s89, v0
	v_or_b32_e32 v191, s90, v1
	v_or_b32_e32 v192, s91, v0
	v_or_b32_e32 v193, s6, v1
	v_or_b32_e32 v194, s7, v0
	v_add_u32_e32 v136, s9, v116
	v_mad_u64_u32 v[134:135], s[62:63], v134, s76, v[22:23]
	v_add_u32_e32 v140, s9, v181
	v_add_u32_e32 v138, s1, v182
	v_add_u32_e32 v144, s9, v183
	v_add_u32_e32 v142, s1, v184
	v_add_u32_e32 v148, s9, v185
	v_add_u32_e32 v146, s1, v186
	v_add_u32_e32 v166, s9, v187
	v_add_u32_e32 v150, s1, v188
	v_add_u32_e32 v170, s9, v189
	v_add_u32_e32 v168, s1, v190
	v_add_u32_e32 v174, s9, v191
	v_add_u32_e32 v172, s1, v192
	v_add_u32_e32 v178, s9, v193
	v_add_u32_e32 v176, s1, v194
	v_mad_u64_u32 v[136:137], s[62:63], v136, s76, v[22:23]
	v_mad_u64_u32 v[138:139], s[62:63], v138, s76, v[22:23]
	v_mad_u64_u32 v[140:141], s[62:63], v140, s76, v[22:23]
	v_mad_u64_u32 v[142:143], s[62:63], v142, s76, v[22:23]
	v_mad_u64_u32 v[144:145], s[62:63], v144, s76, v[22:23]
	v_mad_u64_u32 v[146:147], s[62:63], v146, s76, v[22:23]
	v_mad_u64_u32 v[148:149], s[62:63], v148, s76, v[22:23]
	v_mad_u64_u32 v[150:151], s[62:63], v150, s76, v[22:23]
	v_mad_u64_u32 v[166:167], s[62:63], v166, s76, v[22:23]
	v_mad_u64_u32 v[168:169], s[62:63], v168, s76, v[22:23]
	v_mad_u64_u32 v[170:171], s[62:63], v170, s76, v[22:23]
	v_mad_u64_u32 v[172:173], s[62:63], v172, s76, v[22:23]
	v_mad_u64_u32 v[174:175], s[62:63], v174, s76, v[22:23]
	v_mad_u64_u32 v[176:177], s[62:63], v176, s76, v[22:23]
	v_mad_u64_u32 v[178:179], s[62:63], v178, s76, v[22:23]
	global_load_dword v195, v[134:135], off
	global_load_dword v196, v[136:137], off
	global_load_dword v197, v[138:139], off
	global_load_dword v198, v[140:141], off
	global_load_dword v199, v[142:143], off
	global_load_dword v200, v[144:145], off
	global_load_dword v201, v[146:147], off
	global_load_dword v202, v[148:149], off
	global_load_dword v203, v[150:151], off
	global_load_dword v204, v[166:167], off
	global_load_dword v205, v[168:169], off
	global_load_dword v206, v[170:171], off
	global_load_dword v207, v[172:173], off
	global_load_dword v208, v[174:175], off
	global_load_dword v209, v[176:177], off
	global_load_dword v210, v[178:179], off
	s_add_i32 s58, s58, 16
	s_add_i32 s10, s10, 16
	s_add_i32 s59, s59, -16
	v_mad_u64_u32 v[24:25], s[62:63], v70, s70, v[2:3]
	v_mad_u64_u32 v[26:27], s[62:63], v6, s70, v[2:3]
	v_mad_u64_u32 v[28:29], s[62:63], v72, s70, v[2:3]
	v_mad_u64_u32 v[30:31], s[62:63], v71, s70, v[2:3]
	v_mad_u64_u32 v[32:33], s[62:63], v74, s70, v[2:3]
	v_mad_u64_u32 v[34:35], s[62:63], v73, s70, v[2:3]
	v_mad_u64_u32 v[36:37], s[62:63], v76, s70, v[2:3]
	v_mad_u64_u32 v[38:39], s[62:63], v75, s70, v[2:3]
	v_mad_u64_u32 v[40:41], s[62:63], v78, s70, v[2:3]
	v_mad_u64_u32 v[56:57], s[62:63], v77, s70, v[2:3]
	v_mad_u64_u32 v[58:59], s[62:63], v80, s70, v[2:3]
	v_mad_u64_u32 v[60:61], s[62:63], v79, s70, v[2:3]
	v_mad_u64_u32 v[62:63], s[62:63], v82, s70, v[2:3]
	v_mad_u64_u32 v[64:65], s[62:63], v81, s70, v[2:3]
	v_mad_u64_u32 v[66:67], s[62:63], v84, s70, v[2:3]
	v_mad_u64_u32 v[68:69], s[62:63], v83, s70, v[2:3]
	s_waitcnt vmcnt(31)
; #define LAS __attribute__((address_space(3)))
; __device__ __forceinline__ unsigned pk_bf16(float lo, float hi) { f32x2 v = {lo, hi}; bf16x2_t b = __builtin_convertvector(v, bf16x2_t); return __builtin_bit_cast(unsigned, b); }
; __device__ __forceinline__ void transpose_item(const float* __restrict__ W, int K, int N, int NV, bf16_t* __restrict__ WT, LAS float* scr, int item, int nblk, int lane, int mode, const float* __restrict__ kscale) {
;     ...
;     for (int i = 0; i < 32; ++i) { const int kk = 2 * i + (lane >> 5); float v = valid ? W[(size_t)(k0 + kk) * N + ns] : 0.f; if (kscale) v *= kscale[k0 + kk]; scr[kk * 33 + (lane & 31)] = v; }
;     asm volatile("s_waitcnt lgkmcnt(0)" ::: "memory");
;     const int c = lane & 7;
; #pragma unroll
;     for (int j = 0; j < 4; ++j) { const int n = (lane >> 3) + 8 * j; const LAS float* s = scr + (8 * c) * 33 + n;
;         u32x4 o; o.x = pk_bf16(s[0 * 33], s[1 * 33]); o.y = pk_bf16(s[2 * 33], s[3 * 33]); o.z = pk_bf16(s[4 * 33], s[5 * 33]); o.w = pk_bf16(s[6 * 33], s[7 * 33]);
;         *(u32x4*)(WT + (size_t)(n0 + n) * K + k0 + 8 * c) = o; }
;     asm volatile("s_waitcnt lgkmcnt(0)" ::: "memory");
	ds_write_b32 v24, v85
	s_waitcnt vmcnt(30)
	ds_write_b32 v26, v86
	s_waitcnt vmcnt(29)
	ds_write_b32 v28, v87
	s_waitcnt vmcnt(28)
	ds_write_b32 v30, v88
	s_waitcnt vmcnt(27)
	ds_write_b32 v32, v89
	s_waitcnt vmcnt(26)
	ds_write_b32 v34, v90
	s_waitcnt vmcnt(25)
	ds_write_b32 v36, v91
	s_waitcnt vmcnt(24)
	ds_write_b32 v38, v92
	s_waitcnt vmcnt(23)
	ds_write_b32 v40, v93
	s_waitcnt vmcnt(22)
	ds_write_b32 v56, v94
	s_waitcnt vmcnt(21)
	ds_write_b32 v58, v95
	s_waitcnt vmcnt(20)
	ds_write_b32 v60, v96
	s_waitcnt vmcnt(19)
	ds_write_b32 v62, v97
	s_waitcnt vmcnt(18)
	ds_write_b32 v64, v98
	s_waitcnt vmcnt(17)
	ds_write_b32 v66, v99
	s_waitcnt vmcnt(16)
	ds_write_b32 v68, v100
	v_mad_u64_u32 v[134:135], s[62:63], v180, s70, v[2:3]
	v_mad_u64_u32 v[136:137], s[62:63], v116, s70, v[2:3]
	v_mad_u64_u32 v[138:139], s[62:63], v182, s70, v[2:3]
	v_mad_u64_u32 v[140:141], s[62:63], v181, s70, v[2:3]
	v_mad_u64_u32 v[142:143], s[62:63], v184, s70, v[2:3]
	v_mad_u64_u32 v[144:145], s[62:63], v183, s70, v[2:3]
	v_mad_u64_u32 v[146:147], s[62:63], v186, s70, v[2:3]
	v_mad_u64_u32 v[148:149], s[62:63], v185, s70, v[2:3]
	v_mad_u64_u32 v[150:151], s[62:63], v188, s70, v[2:3]
	v_mad_u64_u32 v[166:167], s[62:63], v187, s70, v[2:3]
	v_mad_u64_u32 v[168:169], s[62:63], v190, s70, v[2:3]
	v_mad_u64_u32 v[170:171], s[62:63], v189, s70, v[2:3]
	v_mad_u64_u32 v[172:173], s[62:63], v192, s70, v[2:3]
	v_mad_u64_u32 v[174:175], s[62:63], v191, s70, v[2:3]
	v_mad_u64_u32 v[176:177], s[62:63], v194, s70, v[2:3]
	v_mad_u64_u32 v[178:179], s[62:63], v193, s70, v[2:3]
	s_waitcnt vmcnt(15)
	ds_write_b32 v134, v195
	s_waitcnt vmcnt(14)
	ds_write_b32 v136, v196
	s_waitcnt vmcnt(13)
	ds_write_b32 v138, v197
	s_waitcnt vmcnt(12)
	ds_write_b32 v140, v198
	s_waitcnt vmcnt(11)
	ds_write_b32 v142, v199
	s_waitcnt vmcnt(10)
	ds_write_b32 v144, v200
	s_waitcnt vmcnt(9)
	ds_write_b32 v146, v201
	s_waitcnt vmcnt(8)
	ds_write_b32 v148, v202
	s_waitcnt vmcnt(7)
	ds_write_b32 v150, v203
	s_waitcnt vmcnt(6)
	ds_write_b32 v166, v204
	s_waitcnt vmcnt(5)
	ds_write_b32 v168, v205
	s_waitcnt vmcnt(4)
	ds_write_b32 v170, v206
	s_waitcnt vmcnt(3)
	ds_write_b32 v172, v207
	s_waitcnt vmcnt(2)
	ds_write_b32 v174, v208
	s_waitcnt vmcnt(1)
	ds_write_b32 v176, v209
	s_waitcnt vmcnt(0)
	ds_write_b32 v178, v210
	s_waitcnt lgkmcnt(0)
	ds_read2_b32 v[26:27], v42 offset0:33 offset1:41
	ds_read2_b32 v[28:29], v42 offset1:8
	ds_read2_b32 v[30:31], v42 offset0:66 offset1:74
	ds_read2_b32 v[32:33], v42 offset0:99 offset1:107
	ds_read2_b32 v[34:35], v42 offset0:132 offset1:140
	ds_read2_b32 v[36:37], v42 offset0:165 offset1:173
	ds_read2_b32 v[38:39], v42 offset0:198 offset1:206
	ds_read2_b32 v[40:41], v42 offset0:231 offset1:239
	s_lshl_b32 s10, s1, 1
	v_or_b32_e32 v6, s0, v21
	v_lshl_add_u64 v[56:57], v[10:11], 0, s[10:11]
	v_lshlrev_b32_e32 v6, 12, v6
	s_waitcnt lgkmcnt(6)
	v_cvt_pk_bf16_f32 v22, v28, v26
	s_waitcnt lgkmcnt(4)
	v_cvt_pk_bf16_f32 v23, v30, v32
	s_waitcnt lgkmcnt(2)
	v_cvt_pk_bf16_f32 v24, v34, v36
	s_waitcnt lgkmcnt(0)
	v_cvt_pk_bf16_f32 v25, v38, v40
	v_lshl_add_u64 v[58:59], v[56:57], 0, v[6:7]
	global_store_dwordx4 v[58:59], v[22:25], off
	v_or_b32_e32 v6, s0, v43
	v_lshlrev_b32_e32 v6, 12, v6
	v_cvt_pk_bf16_f32 v22, v29, v27
	v_cvt_pk_bf16_f32 v23, v31, v33
	v_cvt_pk_bf16_f32 v24, v35, v37
	v_cvt_pk_bf16_f32 v25, v39, v41
	ds_read2_b32 v[28:29], v42 offset0:49 offset1:57
	ds_read2_b32 v[30:31], v42 offset0:16 offset1:24
	ds_read2_b32 v[32:33], v42 offset0:82 offset1:90
	ds_read2_b32 v[34:35], v42 offset0:115 offset1:123
	ds_read2_b32 v[36:37], v42 offset0:148 offset1:156
	ds_read2_b32 v[38:39], v42 offset0:181 offset1:189
	ds_read2_b32 v[40:41], v42 offset0:214 offset1:222
	ds_read2_b32 v[58:59], v42 offset0:247 offset1:255
	v_lshl_add_u64 v[26:27], v[56:57], 0, v[6:7]
	v_or_b32_e32 v6, s0, v44
	v_lshlrev_b32_e32 v6, 12, v6
	global_store_dwordx4 v[26:27], v[22:25], off
	v_lshl_add_u64 v[26:27], v[56:57], 0, v[6:7]
	v_or_b32_e32 v6, s0, v45
	s_waitcnt lgkmcnt(6)
	v_cvt_pk_bf16_f32 v22, v30, v28
	s_waitcnt lgkmcnt(4)
	v_cvt_pk_bf16_f32 v23, v32, v34
	s_waitcnt lgkmcnt(2)
	v_cvt_pk_bf16_f32 v24, v36, v38
	s_waitcnt lgkmcnt(0)
	v_cvt_pk_bf16_f32 v25, v40, v58
	v_lshlrev_b32_e32 v6, 12, v6
	global_store_dwordx4 v[26:27], v[22:25], off
	v_lshl_add_u64 v[26:27], v[56:57], 0, v[6:7]
	v_readlane_b32 s88, v242, 4
	v_cvt_pk_bf16_f32 v22, v31, v29
	v_cvt_pk_bf16_f32 v23, v33, v35
	v_cvt_pk_bf16_f32 v24, v37, v39
	v_cvt_pk_bf16_f32 v25, v41, v59
	global_store_dwordx4 v[26:27], v[22:25], off
	s_waitcnt lgkmcnt(0)
	v_readlane_b32 s89, v242, 5

; __device__ __forceinline__ void transpose_item(const float* __restrict__ W, int K, int N, int NV, bf16_t* __restrict__ WT, LAS float* scr, int item, int nblk, int lane, int mode, const float* __restrict__ kscale) {
;     const int kb = item / nblk, nb = item % nblk, k0 = 64 * kb, n0 = 32 * nb;
;     const int nd = n0 + (lane & 31); const bool valid = nd < NV; const int ns = valid ? srccol(mode, nd) : 0;
; #pragma unroll 8
;     for (int i = 0; i < 32; ++i) { const int kk = 2 * i + (lane >> 5); float v = valid ? W[(size_t)(k0 + kk) * N + ns] : 0.f; if (kscale) v *= kscale[k0 + kk]; scr[kk * 33 + (lane & 31)] = v; }
.LBB0_77:
	s_lshl_b32 s6, s10, 1
	s_lshl_b32 s7, s58, 1
	v_or_b32_e32 v61, s7, v0
	s_add_i32 s34, s6, 4
	s_add_i32 s35, s7, 4
	s_add_i32 s63, s7, 8
	v_add_u32_e32 v6, s1, v61
	v_or_b32_e32 v62, s34, v1
	v_or_b32_e32 v63, s35, v0
	v_mov_b32_e32 v27, v7
	v_or_b32_e32 v60, s6, v1
	s_add_i32 s83, s7, 12
	v_or_b32_e32 v65, s63, v0
	v_lshlrev_b64 v[40:41], 13, v[6:7]
	v_add_u32_e32 v26, s9, v62
	v_add_u32_e32 v6, s1, v63
	v_mov_b32_e32 v25, v7
	s_add_i32 s62, s6, 8
	s_add_i32 s82, s6, 12
	s_add_i32 s87, s7, 16
	v_add_u32_e32 v24, s9, v60
	v_or_b32_e32 v67, s83, v0
	v_lshlrev_b64 v[26:27], 13, v[26:27]
	v_lshlrev_b64 v[56:57], 13, v[6:7]
	v_add_u32_e32 v6, s1, v65
	s_add_i32 s89, s7, 20
	v_or_b32_e32 v64, s62, v1
	v_or_b32_e32 v66, s82, v1
	v_or_b32_e32 v69, s87, v0
	v_lshlrev_b64 v[24:25], 13, v[24:25]
	v_lshl_add_u64 v[40:41], v[22:23], 0, v[40:41]
	v_lshl_add_u64 v[26:27], v[22:23], 0, v[26:27]
	v_lshlrev_b64 v[58:59], 13, v[6:7]
	v_add_u32_e32 v6, s1, v67
	v_mov_b32_e32 v29, v7
	v_mov_b32_e32 v31, v7
	s_add_i32 s86, s6, 16
	s_add_i32 s88, s6, 20
	s_add_i32 s91, s7, 24
	v_or_b32_e32 v71, s89, v0
	v_add_u32_e32 v28, s9, v64
	v_add_u32_e32 v30, s9, v66
	v_lshl_add_u64 v[24:25], v[22:23], 0, v[24:25]
	v_lshl_add_u64 v[56:57], v[22:23], 0, v[56:57]
	global_load_dword v76, v[40:41], off
	global_load_dword v77, v[24:25], off
	global_load_dword v78, v[56:57], off
	global_load_dword v79, v[26:27], off
	v_lshlrev_b64 v[26:27], 13, v[6:7]
	v_add_u32_e32 v6, s1, v69
	s_add_i32 s90, s6, 24
	s_add_i32 s6, s6, 28
	s_add_i32 s7, s7, 28
	v_or_b32_e32 v68, s86, v1
	v_or_b32_e32 v70, s88, v1
	v_or_b32_e32 v73, s91, v0
	v_lshlrev_b64 v[28:29], 13, v[28:29]
	v_lshlrev_b64 v[30:31], 13, v[30:31]
	v_lshl_add_u64 v[24:25], v[22:23], 0, v[58:59]
	v_lshl_add_u64 v[26:27], v[22:23], 0, v[26:27]
	v_lshlrev_b64 v[40:41], 13, v[6:7]
	v_add_u32_e32 v6, s1, v71
	v_mov_b32_e32 v33, v7
	v_mov_b32_e32 v35, v7
	v_or_b32_e32 v72, s90, v1
	v_or_b32_e32 v74, s6, v1
	v_or_b32_e32 v75, s7, v0
	v_add_u32_e32 v32, s9, v68
	v_add_u32_e32 v34, s9, v70
	v_lshl_add_u64 v[28:29], v[22:23], 0, v[28:29]
	v_lshl_add_u64 v[30:31], v[22:23], 0, v[30:31]
	global_load_dword v80, v[24:25], off
	global_load_dword v81, v[28:29], off
	global_load_dword v82, v[26:27], off
	global_load_dword v83, v[30:31], off
	v_lshlrev_b64 v[26:27], 13, v[6:7]
	v_add_u32_e32 v6, s1, v73
	v_mov_b32_e32 v37, v7
	v_mov_b32_e32 v39, v7
	v_add_u32_e32 v36, s9, v72
	v_add_u32_e32 v38, s9, v74
	v_lshlrev_b64 v[32:33], 13, v[32:33]
	v_lshlrev_b64 v[34:35], 13, v[34:35]
	v_lshl_add_u64 v[24:25], v[22:23], 0, v[40:41]
	v_lshl_add_u64 v[26:27], v[22:23], 0, v[26:27]
	v_lshlrev_b64 v[28:29], 13, v[6:7]
	v_add_u32_e32 v6, s1, v75
	v_lshlrev_b64 v[36:37], 13, v[36:37]
	v_lshlrev_b64 v[38:39], 13, v[38:39]
	v_lshl_add_u64 v[32:33], v[22:23], 0, v[32:33]
	v_lshl_add_u64 v[34:35], v[22:23], 0, v[34:35]
	global_load_dword v84, v[24:25], off
	global_load_dword v85, v[32:33], off
	global_load_dword v86, v[26:27], off
	global_load_dword v87, v[34:35], off
	v_lshl_add_u64 v[24:25], v[22:23], 0, v[28:29]
	v_lshlrev_b64 v[26:27], 13, v[6:7]
	v_lshl_add_u64 v[36:37], v[22:23], 0, v[36:37]
	v_lshl_add_u64 v[38:39], v[22:23], 0, v[38:39]
	v_lshl_add_u64 v[26:27], v[22:23], 0, v[26:27]
	global_load_dword v6, v[24:25], off
	global_load_dword v88, v[36:37], off
	global_load_dword v89, v[26:27], off
	global_load_dword v90, v[38:39], off
	s_add_i32 s58, s58, 16
	s_add_i32 s10, s10, 16
	s_add_i32 s59, s59, -16
	v_mov_b32_e32 v117, v7
	s_lshl_b32 s6, s10, 1
	s_lshl_b32 s7, s58, 1
	v_or_b32_e32 v171, s7, v0
	s_add_i32 s34, s6, 4
	s_add_i32 s35, s7, 4
	s_add_i32 s63, s7, 8
	v_add_u32_e32 v116, s1, v171
	v_or_b32_e32 v172, s34, v1
	v_or_b32_e32 v173, s35, v0
	v_mov_b32_e32 v137, v7
	v_or_b32_e32 v170, s6, v1
	s_add_i32 s83, s7, 12
	v_or_b32_e32 v175, s63, v0
	v_lshlrev_b64 v[150:151], 13, v[116:117]
	v_add_u32_e32 v136, s9, v172
	v_add_u32_e32 v116, s1, v173
	v_mov_b32_e32 v135, v7
	s_add_i32 s62, s6, 8
	s_add_i32 s82, s6, 12
	s_add_i32 s87, s7, 16
	v_add_u32_e32 v134, s9, v170
	v_or_b32_e32 v177, s83, v0
	v_lshlrev_b64 v[136:137], 13, v[136:137]
	v_lshlrev_b64 v[166:167], 13, v[116:117]
	v_add_u32_e32 v116, s1, v175
	s_add_i32 s89, s7, 20
	v_or_b32_e32 v174, s62, v1
	v_or_b32_e32 v176, s82, v1
	v_or_b32_e32 v179, s87, v0
	v_lshlrev_b64 v[134:135], 13, v[134:135]
	v_lshl_add_u64 v[150:151], v[22:23], 0, v[150:151]
	v_lshl_add_u64 v[136:137], v[22:23], 0, v[136:137]
	v_lshlrev_b64 v[168:169], 13, v[116:117]
	v_add_u32_e32 v116, s1, v177
	v_mov_b32_e32 v139, v7
	v_mov_b32_e32 v141, v7
	s_add_i32 s86, s6, 16
	s_add_i32 s88, s6, 20
	s_add_i32 s91, s7, 24
	v_or_b32_e32 v181, s89, v0
	v_add_u32_e32 v138, s9, v174
	v_add_u32_e32 v140, s9, v176
	v_lshl_add_u64 v[134:135], v[22:23], 0, v[134:135]
	v_lshl_add_u64 v[166:167], v[22:23], 0, v[166:167]
	global_load_dword v186, v[150:151], off
	global_load_dword v187, v[134:135], off
	global_load_dword v188, v[166:167], off
	global_load_dword v189, v[136:137], off
	v_lshlrev_b64 v[136:137], 13, v[116:117]
	v_add_u32_e32 v116, s1, v179
	s_add_i32 s90, s6, 24
	s_add_i32 s6, s6, 28
	s_add_i32 s7, s7, 28
	v_or_b32_e32 v178, s86, v1
	v_or_b32_e32 v180, s88, v1
	v_or_b32_e32 v183, s91, v0
	v_lshlrev_b64 v[138:139], 13, v[138:139]
	v_lshlrev_b64 v[140:141], 13, v[140:141]
	v_lshl_add_u64 v[134:135], v[22:23], 0, v[168:169]
	v_lshl_add_u64 v[136:137], v[22:23], 0, v[136:137]
	v_lshlrev_b64 v[150:151], 13, v[116:117]
	v_add_u32_e32 v116, s1, v181
	v_mov_b32_e32 v143, v7
	v_mov_b32_e32 v145, v7
	v_or_b32_e32 v182, s90, v1
	v_or_b32_e32 v184, s6, v1
	v_or_b32_e32 v185, s7, v0
	v_add_u32_e32 v142, s9, v178
	v_add_u32_e32 v144, s9, v180
; #define LAS __attribute__((address_space(3)))
; __device__ __forceinline__ unsigned pk_bf16(float lo, float hi) { f32x2 v = {lo, hi}; bf16x2_t b = __builtin_convertvector(v, bf16x2_t); return __builtin_bit_cast(unsigned, b); }
; __device__ __forceinline__ void transpose_item(const float* __restrict__ W, int K, int N, int NV, bf16_t* __restrict__ WT, LAS float* scr, int item, int nblk, int lane, int mode, const float* __restrict__ kscale) {
;     ...
;     for (int i = 0; i < 32; ++i) { const int kk = 2 * i + (lane >> 5); float v = valid ? W[(size_t)(k0 + kk) * N + ns] : 0.f; if (kscale) v *= kscale[k0 + kk]; scr[kk * 33 + (lane & 31)] = v; }
;     asm volatile("s_waitcnt lgkmcnt(0)" ::: "memory");
;     const int c = lane & 7;
; #pragma unroll
;     for (int j = 0; j < 4; ++j) { const int n = (lane >> 3) + 8 * j; const LAS float* s = scr + (8 * c) * 33 + n;
;         u32x4 o; o.x = pk_bf16(s[0 * 33], s[1 * 33]); o.y = pk_bf16(s[2 * 33], s[3 * 33]); o.z = pk_bf16(s[4 * 33], s[5 * 33]); o.w = pk_bf16(s[6 * 33], s[7 * 33]);
;         *(u32x4*)(WT + (size_t)(n0 + n) * K + k0 + 8 * c) = o; }
;     asm volatile("s_waitcnt lgkmcnt(0)" ::: "memory");
	v_lshl_add_u64 v[138:139], v[22:23], 0, v[138:139]
	v_lshl_add_u64 v[140:141], v[22:23], 0, v[140:141]
	global_load_dword v190, v[134:135], off
	global_load_dword v191, v[138:139], off
	global_load_dword v192, v[136:137], off
	global_load_dword v193, v[140:141], off
	v_lshlrev_b64 v[136:137], 13, v[116:117]
	v_add_u32_e32 v116, s1, v183
	v_mov_b32_e32 v147, v7
	v_mov_b32_e32 v149, v7
	v_add_u32_e32 v146, s9, v182
	v_add_u32_e32 v148, s9, v184
	v_lshlrev_b64 v[142:143], 13, v[142:143]
	v_lshlrev_b64 v[144:145], 13, v[144:145]
	v_lshl_add_u64 v[134:135], v[22:23], 0, v[150:151]
	v_lshl_add_u64 v[136:137], v[22:23], 0, v[136:137]
	v_lshlrev_b64 v[138:139], 13, v[116:117]
	v_add_u32_e32 v116, s1, v185
	v_lshlrev_b64 v[146:147], 13, v[146:147]
	v_lshlrev_b64 v[148:149], 13, v[148:149]
	v_lshl_add_u64 v[142:143], v[22:23], 0, v[142:143]
	v_lshl_add_u64 v[144:145], v[22:23], 0, v[144:145]
	global_load_dword v194, v[134:135], off
	global_load_dword v195, v[142:143], off
	global_load_dword v196, v[136:137], off
	global_load_dword v197, v[144:145], off
	v_lshl_add_u64 v[134:135], v[22:23], 0, v[138:139]
	v_lshlrev_b64 v[136:137], 13, v[116:117]
	v_lshl_add_u64 v[146:147], v[22:23], 0, v[146:147]
	v_lshl_add_u64 v[148:149], v[22:23], 0, v[148:149]
	v_lshl_add_u64 v[136:137], v[22:23], 0, v[136:137]
	global_load_dword v116, v[134:135], off
	global_load_dword v198, v[146:147], off
	global_load_dword v199, v[136:137], off
	global_load_dword v200, v[148:149], off
	s_add_i32 s58, s58, 16
	s_add_i32 s10, s10, 16
	s_add_i32 s59, s59, -16
	v_mad_u64_u32 v[24:25], s[62:63], v61, s70, v[2:3]
	v_mad_u64_u32 v[26:27], s[62:63], v60, s70, v[2:3]
	v_mad_u64_u32 v[28:29], s[62:63], v63, s70, v[2:3]
	v_mad_u64_u32 v[30:31], s[62:63], v62, s70, v[2:3]
	v_mad_u64_u32 v[32:33], s[62:63], v65, s70, v[2:3]
	v_mad_u64_u32 v[34:35], s[62:63], v64, s70, v[2:3]
	v_mad_u64_u32 v[36:37], s[62:63], v67, s70, v[2:3]
	v_mad_u64_u32 v[38:39], s[62:63], v66, s70, v[2:3]
	v_mad_u64_u32 v[40:41], s[62:63], v69, s70, v[2:3]
	v_mad_u64_u32 v[56:57], s[62:63], v68, s70, v[2:3]
	v_mad_u64_u32 v[58:59], s[62:63], v71, s70, v[2:3]
	v_mad_u64_u32 v[60:61], s[62:63], v70, s70, v[2:3]
	v_mad_u64_u32 v[62:63], s[62:63], v73, s70, v[2:3]
	v_mad_u64_u32 v[64:65], s[62:63], v72, s70, v[2:3]
	v_mad_u64_u32 v[66:67], s[62:63], v75, s70, v[2:3]
	v_mad_u64_u32 v[68:69], s[62:63], v74, s70, v[2:3]
	s_waitcnt vmcnt(31)
	ds_write_b32 v24, v76
	s_waitcnt vmcnt(30)
	ds_write_b32 v26, v77
	s_waitcnt vmcnt(29)
	ds_write_b32 v28, v78
	s_waitcnt vmcnt(28)
	ds_write_b32 v30, v79
	s_waitcnt vmcnt(27)
	ds_write_b32 v32, v80
	s_waitcnt vmcnt(26)
	ds_write_b32 v34, v81
	s_waitcnt vmcnt(25)
	ds_write_b32 v36, v82
	s_waitcnt vmcnt(24)
	ds_write_b32 v38, v83
	s_waitcnt vmcnt(23)
	ds_write_b32 v40, v84
	s_waitcnt vmcnt(22)
	ds_write_b32 v56, v85
	s_waitcnt vmcnt(21)
	ds_write_b32 v58, v86
	s_waitcnt vmcnt(20)
	ds_write_b32 v60, v87
	s_waitcnt vmcnt(19)
	ds_write_b32 v62, v6
	s_waitcnt vmcnt(18)
	ds_write_b32 v64, v88
	s_waitcnt vmcnt(17)
	ds_write_b32 v66, v89
	s_waitcnt vmcnt(16)
	ds_write_b32 v68, v90
	v_mad_u64_u32 v[134:135], s[62:63], v171, s70, v[2:3]
	v_mad_u64_u32 v[136:137], s[62:63], v170, s70, v[2:3]
	v_mad_u64_u32 v[138:139], s[62:63], v173, s70, v[2:3]
	v_mad_u64_u32 v[140:141], s[62:63], v172, s70, v[2:3]
	v_mad_u64_u32 v[142:143], s[62:63], v175, s70, v[2:3]
	v_mad_u64_u32 v[144:145], s[62:63], v174, s70, v[2:3]
	v_mad_u64_u32 v[146:147], s[62:63], v177, s70, v[2:3]
	v_mad_u64_u32 v[148:149], s[62:63], v176, s70, v[2:3]
	v_mad_u64_u32 v[150:151], s[62:63], v179, s70, v[2:3]
	v_mad_u64_u32 v[166:167], s[62:63], v178, s70, v[2:3]
	v_mad_u64_u32 v[168:169], s[62:63], v181, s70, v[2:3]
	v_mad_u64_u32 v[170:171], s[62:63], v180, s70, v[2:3]
	v_mad_u64_u32 v[172:173], s[62:63], v183, s70, v[2:3]
	v_mad_u64_u32 v[174:175], s[62:63], v182, s70, v[2:3]
	v_mad_u64_u32 v[176:177], s[62:63], v185, s70, v[2:3]
	v_mad_u64_u32 v[178:179], s[62:63], v184, s70, v[2:3]
	s_waitcnt vmcnt(15)
	ds_write_b32 v134, v186
	s_waitcnt vmcnt(14)
	ds_write_b32 v136, v187
	s_waitcnt vmcnt(13)
	ds_write_b32 v138, v188
	s_waitcnt vmcnt(12)
	ds_write_b32 v140, v189
	s_waitcnt vmcnt(11)
	ds_write_b32 v142, v190
	s_waitcnt vmcnt(10)
	ds_write_b32 v144, v191
	s_waitcnt vmcnt(9)
	ds_write_b32 v146, v192
	s_waitcnt vmcnt(8)
	ds_write_b32 v148, v193
	s_waitcnt vmcnt(7)
	ds_write_b32 v150, v194
	s_waitcnt vmcnt(6)
	ds_write_b32 v166, v195
	s_waitcnt vmcnt(5)
	ds_write_b32 v168, v196
	s_waitcnt vmcnt(4)
	ds_write_b32 v170, v197
	s_waitcnt vmcnt(3)
	ds_write_b32 v172, v116
	s_waitcnt vmcnt(2)
	ds_write_b32 v174, v198
	s_waitcnt vmcnt(1)
	ds_write_b32 v176, v199
	s_waitcnt vmcnt(0)
	ds_write_b32 v178, v200
	s_waitcnt lgkmcnt(0)
	ds_read2_b32 v[26:27], v42 offset0:33 offset1:41
	ds_read2_b32 v[28:29], v42 offset1:8
	ds_read2_b32 v[30:31], v42 offset0:66 offset1:74
	ds_read2_b32 v[32:33], v42 offset0:99 offset1:107
	ds_read2_b32 v[34:35], v42 offset0:132 offset1:140
	ds_read2_b32 v[36:37], v42 offset0:165 offset1:173
	ds_read2_b32 v[38:39], v42 offset0:198 offset1:206
	ds_read2_b32 v[40:41], v42 offset0:231 offset1:239
	s_lshl_b32 s10, s1, 1
	v_or_b32_e32 v6, s0, v21
	v_lshl_add_u64 v[56:57], v[12:13], 0, s[10:11]
	v_lshlrev_b32_e32 v6, 12, v6
	s_waitcnt lgkmcnt(6)
	v_cvt_pk_bf16_f32 v22, v28, v26
	s_waitcnt lgkmcnt(4)
	v_cvt_pk_bf16_f32 v23, v30, v32
	s_waitcnt lgkmcnt(2)
	v_cvt_pk_bf16_f32 v24, v34, v36
	s_waitcnt lgkmcnt(0)
	v_cvt_pk_bf16_f32 v25, v38, v40
	v_lshl_add_u64 v[58:59], v[56:57], 0, v[6:7]
	global_store_dwordx4 v[58:59], v[22:25], off
	v_or_b32_e32 v6, s0, v43
	v_lshlrev_b32_e32 v6, 12, v6
	v_cvt_pk_bf16_f32 v22, v29, v27
	v_cvt_pk_bf16_f32 v23, v31, v33
	v_cvt_pk_bf16_f32 v24, v35, v37
	v_cvt_pk_bf16_f32 v25, v39, v41
	ds_read2_b32 v[28:29], v42 offset0:49 offset1:57
	ds_read2_b32 v[30:31], v42 offset0:16 offset1:24
	ds_read2_b32 v[32:33], v42 offset0:82 offset1:90
	ds_read2_b32 v[34:35], v42 offset0:115 offset1:123
	ds_read2_b32 v[36:37], v42 offset0:148 offset1:156
	ds_read2_b32 v[38:39], v42 offset0:181 offset1:189
	ds_read2_b32 v[40:41], v42 offset0:214 offset1:222
	ds_read2_b32 v[58:59], v42 offset0:247 offset1:255
	v_lshl_add_u64 v[26:27], v[56:57], 0, v[6:7]
	v_or_b32_e32 v6, s0, v44
	v_lshlrev_b32_e32 v6, 12, v6
	global_store_dwordx4 v[26:27], v[22:25], off
	v_lshl_add_u64 v[26:27], v[56:57], 0, v[6:7]
	v_or_b32_e32 v6, s0, v45
	s_waitcnt lgkmcnt(6)
	v_cvt_pk_bf16_f32 v22, v30, v28
	s_waitcnt lgkmcnt(4)
	v_cvt_pk_bf16_f32 v23, v32, v34
	s_waitcnt lgkmcnt(2)
	v_cvt_pk_bf16_f32 v24, v36, v38
	s_waitcnt lgkmcnt(0)
	v_cvt_pk_bf16_f32 v25, v40, v58
	v_lshlrev_b32_e32 v6, 12, v6
	global_store_dwordx4 v[26:27], v[22:25], off
	v_lshl_add_u64 v[26:27], v[56:57], 0, v[6:7]
	v_readlane_b32 s88, v242, 4
	v_cvt_pk_bf16_f32 v22, v31, v29
	v_cvt_pk_bf16_f32 v23, v33, v35
	v_cvt_pk_bf16_f32 v24, v37, v39
	v_cvt_pk_bf16_f32 v25, v41, v59
	global_store_dwordx4 v[26:27], v[22:25], off
	s_waitcnt lgkmcnt(0)
	v_readlane_b32 s89, v242, 5
